# causal dwconv + silu gate fused into the up-GEMM epilogue (DPP row shifts, rows 0-1 of each 64-row strip fixed up in a small phase) replacing the memory-bound conv phase; + attention stagger
# speedup vs baseline: 1.0367x; 1.0328x over previous
;     __device__ __forceinline__ void operator()(const f32x4 (&acc)[2][2][4][2], const Unit& u, int wr, int wc, int fr, int fq) const {
;         const int row0 = u.pm * BM + wr * 64 + fr, c0 = u.pn * BM + wc * 32 + 8 * fq;
; #pragma unroll
;         for (int ai = 0; ai < 2; ++ai)
; #pragma unroll
;             for (int m = 0; m < 4; ++m) { const int row = row0 + ai * HALF + m * 16; bf16_t* rowp = UP + (size_t)row * 5632 + u.pn * HALF + wc * 32 + 8 * fq;
; #pragma unroll
;                 for (int bj = 0; bj < 2; ++bj) { const u32x4 w = pack8(acc[ai][bj][m][0], acc[ai][bj][m][1]); __builtin_nontemporal_store(w, (u32x4*)(rowp + (size_t)bj * ((size_t)16384 * 5632)));
;                     if (m == 3 && fr >= 14) *(u32x4*)(HALO + ((size_t)(row >> 6) * 2 + (fr - 14)) * 11264 + c0 + bj * HALF) = w; } }
;     }
; __device__ __forceinline__ void phase10(const Args& a, int G, int wv, bool dummy = false) {
;     ...
;         const int rs = it / 22, cs = it % 22, row0 = rs * 64, pn = 2 * cs + (lane >> 5), j = (lane & 31) * 4, col = 256 * pn + j, ch = 128 * pn + j; constexpr size_t VPL = (size_t)16384 * 5632;
;         const f32x4 wg0 = *(const f32x4*)(cw + ch), wg1 = *(const f32x4*)(cw + 11264 + ch), wg2 = *(const f32x4*)(cw + 22528 + ch), bg = *(const f32x4*)(cb + ch);
;         const f32x4 wv0 = *(const f32x4*)(cw + 5632 + ch), wv1 = *(const f32x4*)(cw + 11264 + 5632 + ch), wv2 = *(const f32x4*)(cw + 22528 + 5632 + ch), bv = *(const f32x4*)(cb + 5632 + ch);
;         f32x4 gm2 = {0.f, 0.f, 0.f, 0.f}, gm1 = gm2, vm2 = gm2, vm1 = gm2;
;         if (row0 & 2047) { const bf16_t* hp = HALO + (size_t)(rs - 1) * 2 * 11264 + col;
;             gm2 = bf4(*(const u32x2*)hp); gm1 = bf4(*(const u32x2*)(hp + 11264)); vm2 = bf4(*(const u32x2*)(hp + 128)); vm1 = bf4(*(const u32x2*)(hp + 11264 + 128)); }
;         bf16_t* up = UP + (size_t)row0 * 5632 + ch;
;         for (int t0 = 0; t0 < 64; t0 += 8) {
;             u32x2 gr[8], vr[8];
; #pragma unroll
;             for (int t = 0; t < 8; ++t) { gr[t] = __builtin_nontemporal_load((const u32x2*)(up + (size_t)(t0 + t) * 5632)); vr[t] = __builtin_nontemporal_load((const u32x2*)(up + VPL + (size_t)(t0 + t) * 5632)); }
; #pragma unroll
;             for (int t = 0; t < 8; ++t) { const f32x4 gc = bf4(gr[t]), vc = bf4(vr[t]);
;                 const f32x4 gg = wg0 * gm2 + wg1 * gm1 + wg2 * gc + bg, vv = wv0 * vm2 + wv1 * vm1 + wv2 * vc + bv;
.LBB0_968:
	s_mov_b32 s98, s28
	s_mov_b32 s99, s29
	s_load_dwordx4 s[28:31], s[0:1], 0xa8
	v_lshlrev_b32_e32 v148, 2, v152
	v_add_u32_e32 v149, s52, v150
	v_mul_u32_u24_e32 v149, 0x2c00, v149
	v_lshl_add_u32 v149, v152, 1, v149
	v_mul_u32_u24_e32 v221, 0x5800, v150
	v_lshl_add_u32 v221, v152, 1, v221
	v_add_u32_e32 v220, 0xfffb3000, v221
	v_cmp_gt_u32_e64 s[64:65], 2, v150
	v_mov_b32_e32 v236, 0xbfb8aa3b
	v_mov_b32_e32 v238, 1.0
	v_mov_b32_e32 v239, 1.0
	s_lshl_b32 s21, s99, 9
	s_waitcnt lgkmcnt(0)
	s_add_u32 s100, s28, s21
	s_addc_u32 s101, s29, 0
	global_load_dwordx4 v[156:159], v148, s[100:101]
	global_load_dwordx4 v[160:163], v148, s[100:101] offset:16
	s_add_u32 s36, s100, 0xb000
	s_addc_u32 s37, s101, 0
	global_load_dwordx4 v[164:167], v148, s[36:37]
	global_load_dwordx4 v[168:171], v148, s[36:37] offset:16
	s_add_u32 s36, s100, 0x16000
	s_addc_u32 s37, s101, 0
	global_load_dwordx4 v[172:175], v148, s[36:37]
	global_load_dwordx4 v[176:179], v148, s[36:37] offset:16
	s_add_u32 s36, s100, 0x5800
	s_addc_u32 s37, s101, 0
	global_load_dwordx4 v[188:191], v148, s[36:37]
	global_load_dwordx4 v[192:195], v148, s[36:37] offset:16
	s_add_u32 s36, s100, 0x10800
	s_addc_u32 s37, s101, 0
	global_load_dwordx4 v[196:199], v148, s[36:37]
	global_load_dwordx4 v[200:203], v148, s[36:37] offset:16
	s_add_u32 s36, s100, 0x1b800
	s_addc_u32 s37, s101, 0
	global_load_dwordx4 v[204:207], v148, s[36:37]
	global_load_dwordx4 v[208:211], v148, s[36:37] offset:16
	s_add_u32 s100, s30, s21
	s_addc_u32 s101, s31, 0
	global_load_dwordx4 v[180:183], v148, s[100:101]
	global_load_dwordx4 v[184:187], v148, s[100:101] offset:16
	s_add_u32 s36, s100, 0x5800
	s_addc_u32 s37, s101, 0
	global_load_dwordx4 v[212:215], v148, s[36:37]
	global_load_dwordx4 v[216:219], v148, s[36:37] offset:16
	s_lshl_b32 s63, s98, 2
	s_lshr_b32 s66, s52, 6
	s_add_i32 s63, s63, s66
	s_mul_i32 s63, s63, 0xb000
	s_add_i32 s63, s63, s21
	s_add_u32 s34, s14, s63
	s_addc_u32 s35, s15, 0
	s_add_u32 s36, s12, 0xb000000
	s_addc_u32 s37, s13, 0
	s_add_u32 s36, s36, s63
	s_addc_u32 s37, s37, 0
	v_cvt_pk_bf16_f32 v222, v80, v81
	v_cvt_pk_bf16_f32 v223, v82, v83
	v_cvt_pk_bf16_f32 v224, v72, v73
	v_cvt_pk_bf16_f32 v225, v74, v75
	s_mov_b64 exec, s[2:3]
	global_store_dwordx4 v220, v[222:225], s[34:35]
	s_mov_b64 exec, -1
	v_cvt_pk_bf16_f32 v226, v68, v69
	v_cvt_pk_bf16_f32 v227, v70, v71
	v_cvt_pk_bf16_f32 v228, v64, v65
	v_cvt_pk_bf16_f32 v229, v66, v67
	s_mov_b64 exec, s[2:3]
	global_store_dwordx4 v220, v[226:229], s[34:35] offset:256
	s_mov_b64 exec, -1
	v_cvt_pk_bf16_f32 v230, v124, v125
	v_cvt_pk_bf16_f32 v231, v126, v127
	v_cvt_pk_bf16_f32 v232, v120, v121
	v_cvt_pk_bf16_f32 v233, v122, v123
	s_mov_b64 exec, s[64:65]
	global_store_dwordx4 v221, v[230:233], s[36:37]
	s_mov_b64 exec, -1
	v_cvt_pk_bf16_f32 v240, v116, v117
	v_cvt_pk_bf16_f32 v241, v118, v119
	v_cvt_pk_bf16_f32 v242, v108, v109
	v_cvt_pk_bf16_f32 v243, v110, v111
	s_mov_b64 exec, s[64:65]
	global_store_dwordx4 v221, v[240:243], s[36:37] offset:256
	s_mov_b64 exec, -1
	s_add_u32 s34, s34, 0x16000
	s_addc_u32 s35, s35, 0
	s_add_u32 s36, s36, 0x16000
	s_addc_u32 s37, s37, 0
	v_cvt_pk_bf16_f32 v222, v16, v17
	v_cvt_pk_bf16_f32 v223, v18, v19
	v_cvt_pk_bf16_f32 v224, v8, v9
	v_cvt_pk_bf16_f32 v225, v10, v11
	s_mov_b64 exec, s[2:3]
	global_store_dwordx4 v220, v[222:225], s[34:35]
	s_mov_b64 exec, -1
	v_cvt_pk_bf16_f32 v226, v4, v5
	v_cvt_pk_bf16_f32 v227, v6, v7
	v_cvt_pk_bf16_f32 v228, v0, v1
	v_cvt_pk_bf16_f32 v229, v2, v3
	s_mov_b64 exec, s[2:3]
	global_store_dwordx4 v220, v[226:229], s[34:35] offset:256
	s_mov_b64 exec, -1
	v_cvt_pk_bf16_f32 v230, v60, v61
	v_cvt_pk_bf16_f32 v231, v62, v63
	v_cvt_pk_bf16_f32 v232, v56, v57
	v_cvt_pk_bf16_f32 v233, v58, v59
	s_mov_b64 exec, s[64:65]
	global_store_dwordx4 v221, v[230:233], s[36:37]
	s_mov_b64 exec, -1
	v_cvt_pk_bf16_f32 v240, v52, v53
	v_cvt_pk_bf16_f32 v241, v54, v55
	v_cvt_pk_bf16_f32 v242, v44, v45
	v_cvt_pk_bf16_f32 v243, v46, v47
	s_mov_b64 exec, s[64:65]
	global_store_dwordx4 v221, v[240:243], s[36:37] offset:256
	s_mov_b64 exec, -1
	s_waitcnt vmcnt(8)
	s_nop 4
	s_mul_i32 s63, s98, 0x2c0000
	s_lshl_b32 s66, s99, 8
	s_add_u32 s63, s63, s66
	s_add_u32 s100, s12, s63
	s_addc_u32 s101, s13, 0
	v_pk_fma_f32 v[232:233], v[80:81], v[172:173], v[180:181]
	v_pk_fma_f32 v[234:235], v[68:69], v[204:205], v[212:213]
	s_nop 1
	v_fmac_f32_dpp v232, v80, v164 row_shr:1 row_mask:0xf bank_mask:0xf
	v_fmac_f32_dpp v233, v81, v165 row_shr:1 row_mask:0xf bank_mask:0xf
	v_fmac_f32_dpp v234, v68, v196 row_shr:1 row_mask:0xf bank_mask:0xf
	v_fmac_f32_dpp v235, v69, v197 row_shr:1 row_mask:0xf bank_mask:0xf
	v_fmac_f32_dpp v232, v80, v156 row_shr:2 row_mask:0xf bank_mask:0xf
	v_fmac_f32_dpp v233, v81, v157 row_shr:2 row_mask:0xf bank_mask:0xf
	v_fmac_f32_dpp v234, v68, v188 row_shr:2 row_mask:0xf bank_mask:0xf
	v_fmac_f32_dpp v235, v69, v189 row_shr:2 row_mask:0xf bank_mask:0xf
	v_fmac_f32_dpp v232, v96, v164 row_shl:15 row_mask:0xf bank_mask:0xf
	v_fmac_f32_dpp v233, v97, v165 row_shl:15 row_mask:0xf bank_mask:0xf
	v_fmac_f32_dpp v234, v84, v196 row_shl:15 row_mask:0xf bank_mask:0xf
	v_fmac_f32_dpp v235, v85, v197 row_shl:15 row_mask:0xf bank_mask:0xf
	v_fmac_f32_dpp v232, v96, v156 row_shl:14 row_mask:0xf bank_mask:0xf
	v_fmac_f32_dpp v233, v97, v157 row_shl:14 row_mask:0xf bank_mask:0xf
	v_fmac_f32_dpp v234, v84, v188 row_shl:14 row_mask:0xf bank_mask:0xf
	v_fmac_f32_dpp v235, v85, v189 row_shl:14 row_mask:0xf bank_mask:0xf
	v_mul_f32_e32 v246, v236, v232
	v_mul_f32_e32 v247, v236, v233
	v_exp_f32_e32 v246, v246
	v_exp_f32_e32 v247, v247
	s_nop 0
	v_pk_add_f32 v[246:247], v[246:247], v[238:239]
; __device__ __forceinline__ unsigned cvt_pk_bf16(float lo, float hi) { unsigned r; asm("v_cvt_pk_bf16_f32 %0, %1, %2" : "=v"(r) : "v"(lo), "v"(hi)); return r; }
; __device__ __forceinline__ float sigmoid_f(float v) { return __builtin_amdgcn_rcpf(1.0f + __builtin_amdgcn_exp2f(-1.4426950409f * v)); }
; __device__ __forceinline__ f32x4 bf4(u32x2 w) { return (f32x4){bf_lo(w.x), bf_hi(w.x), bf_lo(w.y), bf_hi(w.y)}; }
; __device__ __forceinline__ void phase10(const Args& a, int G, int wv, bool dummy = false) {
;     ...
;             for (int t = 0; t < 8; ++t) { const f32x4 gc = bf4(gr[t]), vc = bf4(vr[t]);
;                 const f32x4 gg = wg0 * gm2 + wg1 * gm1 + wg2 * gc + bg, vv = wv0 * vm2 + wv1 * vm1 + wv2 * vc + bv;
;                 f32x4 o;
; #pragma unroll
;                 for (int e = 0; e < 4; ++e) o[e] = gg[e] * pg8::sigmoid_f(gg[e]) * vv[e];
;                 u32x2 w; w.x = cvt_pk_bf16(o[0], o[1]); w.y = cvt_pk_bf16(o[2], o[3]);
	v_rcp_f32_e32 v246, v246
	v_rcp_f32_e32 v247, v247
	v_pk_mul_f32 v[232:233], v[232:233], v[234:235]
	v_pk_mul_f32 v[232:233], v[232:233], v[246:247]
	v_cvt_pk_bf16_f32 v80, v232, v233
	v_pk_fma_f32 v[232:233], v[96:97], v[172:173], v[180:181]
	v_pk_fma_f32 v[234:235], v[84:85], v[204:205], v[212:213]
	s_nop 1
	v_fmac_f32_dpp v232, v96, v164 row_shr:1 row_mask:0xf bank_mask:0xf
	v_fmac_f32_dpp v233, v97, v165 row_shr:1 row_mask:0xf bank_mask:0xf
	v_fmac_f32_dpp v234, v84, v196 row_shr:1 row_mask:0xf bank_mask:0xf
	v_fmac_f32_dpp v235, v85, v197 row_shr:1 row_mask:0xf bank_mask:0xf
	v_fmac_f32_dpp v232, v96, v156 row_shr:2 row_mask:0xf bank_mask:0xf
	v_fmac_f32_dpp v233, v97, v157 row_shr:2 row_mask:0xf bank_mask:0xf
	v_fmac_f32_dpp v234, v84, v188 row_shr:2 row_mask:0xf bank_mask:0xf
	v_fmac_f32_dpp v235, v85, v189 row_shr:2 row_mask:0xf bank_mask:0xf
	v_fmac_f32_dpp v232, v112, v164 row_shl:15 row_mask:0xf bank_mask:0xf
	v_fmac_f32_dpp v233, v113, v165 row_shl:15 row_mask:0xf bank_mask:0xf
	v_fmac_f32_dpp v234, v100, v196 row_shl:15 row_mask:0xf bank_mask:0xf
	v_fmac_f32_dpp v235, v101, v197 row_shl:15 row_mask:0xf bank_mask:0xf
	v_fmac_f32_dpp v232, v112, v156 row_shl:14 row_mask:0xf bank_mask:0xf
	v_fmac_f32_dpp v233, v113, v157 row_shl:14 row_mask:0xf bank_mask:0xf
	v_fmac_f32_dpp v234, v100, v188 row_shl:14 row_mask:0xf bank_mask:0xf
	v_fmac_f32_dpp v235, v101, v189 row_shl:14 row_mask:0xf bank_mask:0xf
	v_mul_f32_e32 v246, v236, v232
	v_mul_f32_e32 v247, v236, v233
	v_exp_f32_e32 v246, v246
	v_exp_f32_e32 v247, v247
	s_nop 0
	v_pk_add_f32 v[246:247], v[246:247], v[238:239]
	v_rcp_f32_e32 v246, v246
	v_rcp_f32_e32 v247, v247
	v_pk_mul_f32 v[232:233], v[232:233], v[234:235]
	v_pk_mul_f32 v[232:233], v[232:233], v[246:247]
	v_cvt_pk_bf16_f32 v96, v232, v233
	v_pk_fma_f32 v[232:233], v[112:113], v[172:173], v[180:181]
	v_pk_fma_f32 v[234:235], v[100:101], v[204:205], v[212:213]
	s_nop 1
	v_fmac_f32_dpp v232, v112, v164 row_shr:1 row_mask:0xf bank_mask:0xf
	v_fmac_f32_dpp v233, v113, v165 row_shr:1 row_mask:0xf bank_mask:0xf
	v_fmac_f32_dpp v234, v100, v196 row_shr:1 row_mask:0xf bank_mask:0xf
	v_fmac_f32_dpp v235, v101, v197 row_shr:1 row_mask:0xf bank_mask:0xf
	v_fmac_f32_dpp v232, v112, v156 row_shr:2 row_mask:0xf bank_mask:0xf
	v_fmac_f32_dpp v233, v113, v157 row_shr:2 row_mask:0xf bank_mask:0xf
	v_fmac_f32_dpp v234, v100, v188 row_shr:2 row_mask:0xf bank_mask:0xf
	v_fmac_f32_dpp v235, v101, v189 row_shr:2 row_mask:0xf bank_mask:0xf
	v_fmac_f32_dpp v232, v124, v164 row_shl:15 row_mask:0xf bank_mask:0xf
	v_fmac_f32_dpp v233, v125, v165 row_shl:15 row_mask:0xf bank_mask:0xf
	v_fmac_f32_dpp v234, v116, v196 row_shl:15 row_mask:0xf bank_mask:0xf
	v_fmac_f32_dpp v235, v117, v197 row_shl:15 row_mask:0xf bank_mask:0xf
	v_fmac_f32_dpp v232, v124, v156 row_shl:14 row_mask:0xf bank_mask:0xf
	v_fmac_f32_dpp v233, v125, v157 row_shl:14 row_mask:0xf bank_mask:0xf
	v_fmac_f32_dpp v234, v116, v188 row_shl:14 row_mask:0xf bank_mask:0xf
	v_fmac_f32_dpp v235, v117, v189 row_shl:14 row_mask:0xf bank_mask:0xf
	v_mul_f32_e32 v246, v236, v232
	v_mul_f32_e32 v247, v236, v233
	v_exp_f32_e32 v246, v246
	v_exp_f32_e32 v247, v247
	s_nop 0
	v_pk_add_f32 v[246:247], v[246:247], v[238:239]
	v_rcp_f32_e32 v246, v246
	v_rcp_f32_e32 v247, v247
	v_pk_mul_f32 v[232:233], v[232:233], v[234:235]
	v_pk_mul_f32 v[232:233], v[232:233], v[246:247]
	v_cvt_pk_bf16_f32 v112, v232, v233
	v_pk_fma_f32 v[232:233], v[124:125], v[172:173], v[180:181]
	v_pk_fma_f32 v[234:235], v[116:117], v[204:205], v[212:213]
	s_nop 1
	v_fmac_f32_dpp v232, v124, v164 row_shr:1 row_mask:0xf bank_mask:0xf
	v_fmac_f32_dpp v233, v125, v165 row_shr:1 row_mask:0xf bank_mask:0xf
	v_fmac_f32_dpp v234, v116, v196 row_shr:1 row_mask:0xf bank_mask:0xf
	v_fmac_f32_dpp v235, v117, v197 row_shr:1 row_mask:0xf bank_mask:0xf
	v_fmac_f32_dpp v232, v124, v156 row_shr:2 row_mask:0xf bank_mask:0xf
	v_fmac_f32_dpp v233, v125, v157 row_shr:2 row_mask:0xf bank_mask:0xf
	v_fmac_f32_dpp v234, v116, v188 row_shr:2 row_mask:0xf bank_mask:0xf
	v_fmac_f32_dpp v235, v117, v189 row_shr:2 row_mask:0xf bank_mask:0xf
	v_mul_f32_e32 v246, v236, v232
	v_mul_f32_e32 v247, v236, v233
	v_exp_f32_e32 v246, v246
	v_exp_f32_e32 v247, v247
	s_nop 0
	v_pk_add_f32 v[246:247], v[246:247], v[238:239]
	v_rcp_f32_e32 v246, v246
	v_rcp_f32_e32 v247, v247
	v_pk_mul_f32 v[232:233], v[232:233], v[234:235]
	v_pk_mul_f32 v[232:233], v[232:233], v[246:247]
	v_cvt_pk_bf16_f32 v124, v232, v233
	v_pk_fma_f32 v[232:233], v[82:83], v[174:175], v[182:183]
	v_pk_fma_f32 v[234:235], v[70:71], v[206:207], v[214:215]
	s_nop 1
	v_fmac_f32_dpp v232, v82, v166 row_shr:1 row_mask:0xf bank_mask:0xf
	v_fmac_f32_dpp v233, v83, v167 row_shr:1 row_mask:0xf bank_mask:0xf
	v_fmac_f32_dpp v234, v70, v198 row_shr:1 row_mask:0xf bank_mask:0xf
	v_fmac_f32_dpp v235, v71, v199 row_shr:1 row_mask:0xf bank_mask:0xf
	v_fmac_f32_dpp v232, v82, v158 row_shr:2 row_mask:0xf bank_mask:0xf
	v_fmac_f32_dpp v233, v83, v159 row_shr:2 row_mask:0xf bank_mask:0xf
	v_fmac_f32_dpp v234, v70, v190 row_shr:2 row_mask:0xf bank_mask:0xf
	v_fmac_f32_dpp v235, v71, v191 row_shr:2 row_mask:0xf bank_mask:0xf
	v_fmac_f32_dpp v232, v98, v166 row_shl:15 row_mask:0xf bank_mask:0xf
	v_fmac_f32_dpp v233, v99, v167 row_shl:15 row_mask:0xf bank_mask:0xf
	v_fmac_f32_dpp v234, v86, v198 row_shl:15 row_mask:0xf bank_mask:0xf
	v_fmac_f32_dpp v235, v87, v199 row_shl:15 row_mask:0xf bank_mask:0xf
	v_fmac_f32_dpp v232, v98, v158 row_shl:14 row_mask:0xf bank_mask:0xf
	v_fmac_f32_dpp v233, v99, v159 row_shl:14 row_mask:0xf bank_mask:0xf
	v_fmac_f32_dpp v234, v86, v190 row_shl:14 row_mask:0xf bank_mask:0xf
; __device__ __forceinline__ unsigned cvt_pk_bf16(float lo, float hi) { unsigned r; asm("v_cvt_pk_bf16_f32 %0, %1, %2" : "=v"(r) : "v"(lo), "v"(hi)); return r; }
; __device__ __forceinline__ float sigmoid_f(float v) { return __builtin_amdgcn_rcpf(1.0f + __builtin_amdgcn_exp2f(-1.4426950409f * v)); }
; __device__ __forceinline__ f32x4 bf4(u32x2 w) { return (f32x4){bf_lo(w.x), bf_hi(w.x), bf_lo(w.y), bf_hi(w.y)}; }
; __device__ __forceinline__ void phase10(const Args& a, int G, int wv, bool dummy = false) {
;     ...
;             for (int t = 0; t < 8; ++t) { const f32x4 gc = bf4(gr[t]), vc = bf4(vr[t]);
;                 const f32x4 gg = wg0 * gm2 + wg1 * gm1 + wg2 * gc + bg, vv = wv0 * vm2 + wv1 * vm1 + wv2 * vc + bv;
;                 f32x4 o;
; #pragma unroll
;                 for (int e = 0; e < 4; ++e) o[e] = gg[e] * pg8::sigmoid_f(gg[e]) * vv[e];
;                 u32x2 w; w.x = cvt_pk_bf16(o[0], o[1]); w.y = cvt_pk_bf16(o[2], o[3]);
	v_fmac_f32_dpp v235, v87, v191 row_shl:14 row_mask:0xf bank_mask:0xf
	v_mul_f32_e32 v246, v236, v232
	v_mul_f32_e32 v247, v236, v233
	v_exp_f32_e32 v246, v246
	v_exp_f32_e32 v247, v247
	s_nop 0
	v_pk_add_f32 v[246:247], v[246:247], v[238:239]
	v_rcp_f32_e32 v246, v246
	v_rcp_f32_e32 v247, v247
	v_pk_mul_f32 v[232:233], v[232:233], v[234:235]
	v_pk_mul_f32 v[232:233], v[232:233], v[246:247]
	v_cvt_pk_bf16_f32 v81, v232, v233
	v_pk_fma_f32 v[232:233], v[98:99], v[174:175], v[182:183]
	v_pk_fma_f32 v[234:235], v[86:87], v[206:207], v[214:215]
	s_nop 1
	v_fmac_f32_dpp v232, v98, v166 row_shr:1 row_mask:0xf bank_mask:0xf
	v_fmac_f32_dpp v233, v99, v167 row_shr:1 row_mask:0xf bank_mask:0xf
	v_fmac_f32_dpp v234, v86, v198 row_shr:1 row_mask:0xf bank_mask:0xf
	v_fmac_f32_dpp v235, v87, v199 row_shr:1 row_mask:0xf bank_mask:0xf
	v_fmac_f32_dpp v232, v98, v158 row_shr:2 row_mask:0xf bank_mask:0xf
	v_fmac_f32_dpp v233, v99, v159 row_shr:2 row_mask:0xf bank_mask:0xf
	v_fmac_f32_dpp v234, v86, v190 row_shr:2 row_mask:0xf bank_mask:0xf
	v_fmac_f32_dpp v235, v87, v191 row_shr:2 row_mask:0xf bank_mask:0xf
	v_fmac_f32_dpp v232, v114, v166 row_shl:15 row_mask:0xf bank_mask:0xf
	v_fmac_f32_dpp v233, v115, v167 row_shl:15 row_mask:0xf bank_mask:0xf
	v_fmac_f32_dpp v234, v102, v198 row_shl:15 row_mask:0xf bank_mask:0xf
	v_fmac_f32_dpp v235, v103, v199 row_shl:15 row_mask:0xf bank_mask:0xf
	v_fmac_f32_dpp v232, v114, v158 row_shl:14 row_mask:0xf bank_mask:0xf
	v_fmac_f32_dpp v233, v115, v159 row_shl:14 row_mask:0xf bank_mask:0xf
	v_fmac_f32_dpp v234, v102, v190 row_shl:14 row_mask:0xf bank_mask:0xf
	v_fmac_f32_dpp v235, v103, v191 row_shl:14 row_mask:0xf bank_mask:0xf
	v_mul_f32_e32 v246, v236, v232
	v_mul_f32_e32 v247, v236, v233
	v_exp_f32_e32 v246, v246
	v_exp_f32_e32 v247, v247
	s_nop 0
	v_pk_add_f32 v[246:247], v[246:247], v[238:239]
	v_rcp_f32_e32 v246, v246
	v_rcp_f32_e32 v247, v247
	v_pk_mul_f32 v[232:233], v[232:233], v[234:235]
	v_pk_mul_f32 v[232:233], v[232:233], v[246:247]
	v_cvt_pk_bf16_f32 v97, v232, v233
	v_pk_fma_f32 v[232:233], v[114:115], v[174:175], v[182:183]
	v_pk_fma_f32 v[234:235], v[102:103], v[206:207], v[214:215]
	s_nop 1
	v_fmac_f32_dpp v232, v114, v166 row_shr:1 row_mask:0xf bank_mask:0xf
	v_fmac_f32_dpp v233, v115, v167 row_shr:1 row_mask:0xf bank_mask:0xf
	v_fmac_f32_dpp v234, v102, v198 row_shr:1 row_mask:0xf bank_mask:0xf
	v_fmac_f32_dpp v235, v103, v199 row_shr:1 row_mask:0xf bank_mask:0xf
	v_fmac_f32_dpp v232, v114, v158 row_shr:2 row_mask:0xf bank_mask:0xf
	v_fmac_f32_dpp v233, v115, v159 row_shr:2 row_mask:0xf bank_mask:0xf
	v_fmac_f32_dpp v234, v102, v190 row_shr:2 row_mask:0xf bank_mask:0xf
	v_fmac_f32_dpp v235, v103, v191 row_shr:2 row_mask:0xf bank_mask:0xf
	v_fmac_f32_dpp v232, v126, v166 row_shl:15 row_mask:0xf bank_mask:0xf
	v_fmac_f32_dpp v233, v127, v167 row_shl:15 row_mask:0xf bank_mask:0xf
	v_fmac_f32_dpp v234, v118, v198 row_shl:15 row_mask:0xf bank_mask:0xf
	v_fmac_f32_dpp v235, v119, v199 row_shl:15 row_mask:0xf bank_mask:0xf
	v_fmac_f32_dpp v232, v126, v158 row_shl:14 row_mask:0xf bank_mask:0xf
	v_fmac_f32_dpp v233, v127, v159 row_shl:14 row_mask:0xf bank_mask:0xf
	v_fmac_f32_dpp v234, v118, v190 row_shl:14 row_mask:0xf bank_mask:0xf
	v_fmac_f32_dpp v235, v119, v191 row_shl:14 row_mask:0xf bank_mask:0xf
	v_mul_f32_e32 v246, v236, v232
	v_mul_f32_e32 v247, v236, v233
	v_exp_f32_e32 v246, v246
	v_exp_f32_e32 v247, v247
	s_nop 0
	v_pk_add_f32 v[246:247], v[246:247], v[238:239]
	v_rcp_f32_e32 v246, v246
	v_rcp_f32_e32 v247, v247
	v_pk_mul_f32 v[232:233], v[232:233], v[234:235]
	v_pk_mul_f32 v[232:233], v[232:233], v[246:247]
	v_cvt_pk_bf16_f32 v113, v232, v233
	v_pk_fma_f32 v[232:233], v[126:127], v[174:175], v[182:183]
	v_pk_fma_f32 v[234:235], v[118:119], v[206:207], v[214:215]
	s_nop 1
	v_fmac_f32_dpp v232, v126, v166 row_shr:1 row_mask:0xf bank_mask:0xf
	v_fmac_f32_dpp v233, v127, v167 row_shr:1 row_mask:0xf bank_mask:0xf
	v_fmac_f32_dpp v234, v118, v198 row_shr:1 row_mask:0xf bank_mask:0xf
	v_fmac_f32_dpp v235, v119, v199 row_shr:1 row_mask:0xf bank_mask:0xf
	v_fmac_f32_dpp v232, v126, v158 row_shr:2 row_mask:0xf bank_mask:0xf
	v_fmac_f32_dpp v233, v127, v159 row_shr:2 row_mask:0xf bank_mask:0xf
	v_fmac_f32_dpp v234, v118, v190 row_shr:2 row_mask:0xf bank_mask:0xf
	v_fmac_f32_dpp v235, v119, v191 row_shr:2 row_mask:0xf bank_mask:0xf
	v_mul_f32_e32 v246, v236, v232
	v_mul_f32_e32 v247, v236, v233
	v_exp_f32_e32 v246, v246
	v_exp_f32_e32 v247, v247
	s_nop 0
	v_pk_add_f32 v[246:247], v[246:247], v[238:239]
	v_rcp_f32_e32 v246, v246
	v_rcp_f32_e32 v247, v247
	v_pk_mul_f32 v[232:233], v[232:233], v[234:235]
	v_pk_mul_f32 v[232:233], v[232:233], v[246:247]
	v_cvt_pk_bf16_f32 v125, v232, v233
	v_pk_fma_f32 v[232:233], v[72:73], v[176:177], v[184:185]
	v_pk_fma_f32 v[234:235], v[64:65], v[208:209], v[216:217]
	s_nop 1
	v_fmac_f32_dpp v232, v72, v168 row_shr:1 row_mask:0xf bank_mask:0xf
	v_fmac_f32_dpp v233, v73, v169 row_shr:1 row_mask:0xf bank_mask:0xf
	v_fmac_f32_dpp v234, v64, v200 row_shr:1 row_mask:0xf bank_mask:0xf
	v_fmac_f32_dpp v235, v65, v201 row_shr:1 row_mask:0xf bank_mask:0xf
	v_fmac_f32_dpp v232, v72, v160 row_shr:2 row_mask:0xf bank_mask:0xf
	v_fmac_f32_dpp v233, v73, v161 row_shr:2 row_mask:0xf bank_mask:0xf
	v_fmac_f32_dpp v234, v64, v192 row_shr:2 row_mask:0xf bank_mask:0xf
	v_fmac_f32_dpp v235, v65, v193 row_shr:2 row_mask:0xf bank_mask:0xf
	v_fmac_f32_dpp v232, v88, v168 row_shl:15 row_mask:0xf bank_mask:0xf
	v_fmac_f32_dpp v233, v89, v169 row_shl:15 row_mask:0xf bank_mask:0xf
	v_fmac_f32_dpp v234, v76, v200 row_shl:15 row_mask:0xf bank_mask:0xf
	v_fmac_f32_dpp v235, v77, v201 row_shl:15 row_mask:0xf bank_mask:0xf
; __device__ __forceinline__ unsigned cvt_pk_bf16(float lo, float hi) { unsigned r; asm("v_cvt_pk_bf16_f32 %0, %1, %2" : "=v"(r) : "v"(lo), "v"(hi)); return r; }
; __device__ __forceinline__ float sigmoid_f(float v) { return __builtin_amdgcn_rcpf(1.0f + __builtin_amdgcn_exp2f(-1.4426950409f * v)); }
; __device__ __forceinline__ f32x4 bf4(u32x2 w) { return (f32x4){bf_lo(w.x), bf_hi(w.x), bf_lo(w.y), bf_hi(w.y)}; }
; __device__ __forceinline__ void phase10(const Args& a, int G, int wv, bool dummy = false) {
;     ...
;             for (int t = 0; t < 8; ++t) { const f32x4 gc = bf4(gr[t]), vc = bf4(vr[t]);
;                 const f32x4 gg = wg0 * gm2 + wg1 * gm1 + wg2 * gc + bg, vv = wv0 * vm2 + wv1 * vm1 + wv2 * vc + bv;
;                 f32x4 o;
; #pragma unroll
;                 for (int e = 0; e < 4; ++e) o[e] = gg[e] * pg8::sigmoid_f(gg[e]) * vv[e];
;                 u32x2 w; w.x = cvt_pk_bf16(o[0], o[1]); w.y = cvt_pk_bf16(o[2], o[3]);
	v_fmac_f32_dpp v232, v88, v160 row_shl:14 row_mask:0xf bank_mask:0xf
	v_fmac_f32_dpp v233, v89, v161 row_shl:14 row_mask:0xf bank_mask:0xf
	v_fmac_f32_dpp v234, v76, v192 row_shl:14 row_mask:0xf bank_mask:0xf
	v_fmac_f32_dpp v235, v77, v193 row_shl:14 row_mask:0xf bank_mask:0xf
	v_mul_f32_e32 v246, v236, v232
	v_mul_f32_e32 v247, v236, v233
	v_exp_f32_e32 v246, v246
	v_exp_f32_e32 v247, v247
	s_nop 0
	v_pk_add_f32 v[246:247], v[246:247], v[238:239]
	v_rcp_f32_e32 v246, v246
	v_rcp_f32_e32 v247, v247
	v_pk_mul_f32 v[232:233], v[232:233], v[234:235]
	v_pk_mul_f32 v[232:233], v[232:233], v[246:247]
	v_cvt_pk_bf16_f32 v82, v232, v233
	v_pk_fma_f32 v[232:233], v[88:89], v[176:177], v[184:185]
	v_pk_fma_f32 v[234:235], v[76:77], v[208:209], v[216:217]
	s_nop 1
	v_fmac_f32_dpp v232, v88, v168 row_shr:1 row_mask:0xf bank_mask:0xf
	v_fmac_f32_dpp v233, v89, v169 row_shr:1 row_mask:0xf bank_mask:0xf
	v_fmac_f32_dpp v234, v76, v200 row_shr:1 row_mask:0xf bank_mask:0xf
	v_fmac_f32_dpp v235, v77, v201 row_shr:1 row_mask:0xf bank_mask:0xf
	v_fmac_f32_dpp v232, v88, v160 row_shr:2 row_mask:0xf bank_mask:0xf
	v_fmac_f32_dpp v233, v89, v161 row_shr:2 row_mask:0xf bank_mask:0xf
	v_fmac_f32_dpp v234, v76, v192 row_shr:2 row_mask:0xf bank_mask:0xf
	v_fmac_f32_dpp v235, v77, v193 row_shr:2 row_mask:0xf bank_mask:0xf
	v_fmac_f32_dpp v232, v104, v168 row_shl:15 row_mask:0xf bank_mask:0xf
	v_fmac_f32_dpp v233, v105, v169 row_shl:15 row_mask:0xf bank_mask:0xf
	v_fmac_f32_dpp v234, v92, v200 row_shl:15 row_mask:0xf bank_mask:0xf
	v_fmac_f32_dpp v235, v93, v201 row_shl:15 row_mask:0xf bank_mask:0xf
	v_fmac_f32_dpp v232, v104, v160 row_shl:14 row_mask:0xf bank_mask:0xf
	v_fmac_f32_dpp v233, v105, v161 row_shl:14 row_mask:0xf bank_mask:0xf
	v_fmac_f32_dpp v234, v92, v192 row_shl:14 row_mask:0xf bank_mask:0xf
	v_fmac_f32_dpp v235, v93, v193 row_shl:14 row_mask:0xf bank_mask:0xf
	v_mul_f32_e32 v246, v236, v232
	v_mul_f32_e32 v247, v236, v233
	v_exp_f32_e32 v246, v246
	v_exp_f32_e32 v247, v247
	s_nop 0
	v_pk_add_f32 v[246:247], v[246:247], v[238:239]
	v_rcp_f32_e32 v246, v246
	v_rcp_f32_e32 v247, v247
	v_pk_mul_f32 v[232:233], v[232:233], v[234:235]
	v_pk_mul_f32 v[232:233], v[232:233], v[246:247]
	v_cvt_pk_bf16_f32 v98, v232, v233
	v_pk_fma_f32 v[232:233], v[104:105], v[176:177], v[184:185]
	v_pk_fma_f32 v[234:235], v[92:93], v[208:209], v[216:217]
	s_nop 1
	v_fmac_f32_dpp v232, v104, v168 row_shr:1 row_mask:0xf bank_mask:0xf
	v_fmac_f32_dpp v233, v105, v169 row_shr:1 row_mask:0xf bank_mask:0xf
	v_fmac_f32_dpp v234, v92, v200 row_shr:1 row_mask:0xf bank_mask:0xf
	v_fmac_f32_dpp v235, v93, v201 row_shr:1 row_mask:0xf bank_mask:0xf
	v_fmac_f32_dpp v232, v104, v160 row_shr:2 row_mask:0xf bank_mask:0xf
	v_fmac_f32_dpp v233, v105, v161 row_shr:2 row_mask:0xf bank_mask:0xf
	v_fmac_f32_dpp v234, v92, v192 row_shr:2 row_mask:0xf bank_mask:0xf
	v_fmac_f32_dpp v235, v93, v193 row_shr:2 row_mask:0xf bank_mask:0xf
	v_fmac_f32_dpp v232, v120, v168 row_shl:15 row_mask:0xf bank_mask:0xf
	v_fmac_f32_dpp v233, v121, v169 row_shl:15 row_mask:0xf bank_mask:0xf
	v_fmac_f32_dpp v234, v108, v200 row_shl:15 row_mask:0xf bank_mask:0xf
	v_fmac_f32_dpp v235, v109, v201 row_shl:15 row_mask:0xf bank_mask:0xf
	v_fmac_f32_dpp v232, v120, v160 row_shl:14 row_mask:0xf bank_mask:0xf
	v_fmac_f32_dpp v233, v121, v161 row_shl:14 row_mask:0xf bank_mask:0xf
	v_fmac_f32_dpp v234, v108, v192 row_shl:14 row_mask:0xf bank_mask:0xf
	v_fmac_f32_dpp v235, v109, v193 row_shl:14 row_mask:0xf bank_mask:0xf
	v_mul_f32_e32 v246, v236, v232
	v_mul_f32_e32 v247, v236, v233
	v_exp_f32_e32 v246, v246
	v_exp_f32_e32 v247, v247
	s_nop 0
	v_pk_add_f32 v[246:247], v[246:247], v[238:239]
	v_rcp_f32_e32 v246, v246
	v_rcp_f32_e32 v247, v247
	v_pk_mul_f32 v[232:233], v[232:233], v[234:235]
	v_pk_mul_f32 v[232:233], v[232:233], v[246:247]
	v_cvt_pk_bf16_f32 v114, v232, v233
	v_pk_fma_f32 v[232:233], v[120:121], v[176:177], v[184:185]
	v_pk_fma_f32 v[234:235], v[108:109], v[208:209], v[216:217]
	s_nop 1
	v_fmac_f32_dpp v232, v120, v168 row_shr:1 row_mask:0xf bank_mask:0xf
	v_fmac_f32_dpp v233, v121, v169 row_shr:1 row_mask:0xf bank_mask:0xf
	v_fmac_f32_dpp v234, v108, v200 row_shr:1 row_mask:0xf bank_mask:0xf
	v_fmac_f32_dpp v235, v109, v201 row_shr:1 row_mask:0xf bank_mask:0xf
	v_fmac_f32_dpp v232, v120, v160 row_shr:2 row_mask:0xf bank_mask:0xf
	v_fmac_f32_dpp v233, v121, v161 row_shr:2 row_mask:0xf bank_mask:0xf
	v_fmac_f32_dpp v234, v108, v192 row_shr:2 row_mask:0xf bank_mask:0xf
	v_fmac_f32_dpp v235, v109, v193 row_shr:2 row_mask:0xf bank_mask:0xf
	v_mul_f32_e32 v246, v236, v232
	v_mul_f32_e32 v247, v236, v233
	v_exp_f32_e32 v246, v246
	v_exp_f32_e32 v247, v247
	s_nop 0
	v_pk_add_f32 v[246:247], v[246:247], v[238:239]
	v_rcp_f32_e32 v246, v246
	v_rcp_f32_e32 v247, v247
	v_pk_mul_f32 v[232:233], v[232:233], v[234:235]
	v_pk_mul_f32 v[232:233], v[232:233], v[246:247]
	v_cvt_pk_bf16_f32 v126, v232, v233
	v_pk_fma_f32 v[232:233], v[74:75], v[178:179], v[186:187]
	v_pk_fma_f32 v[234:235], v[66:67], v[210:211], v[218:219]
	s_nop 1
	v_fmac_f32_dpp v232, v74, v170 row_shr:1 row_mask:0xf bank_mask:0xf
	v_fmac_f32_dpp v233, v75, v171 row_shr:1 row_mask:0xf bank_mask:0xf
	v_fmac_f32_dpp v234, v66, v202 row_shr:1 row_mask:0xf bank_mask:0xf
	v_fmac_f32_dpp v235, v67, v203 row_shr:1 row_mask:0xf bank_mask:0xf
	v_fmac_f32_dpp v232, v74, v162 row_shr:2 row_mask:0xf bank_mask:0xf
	v_fmac_f32_dpp v233, v75, v163 row_shr:2 row_mask:0xf bank_mask:0xf
	v_fmac_f32_dpp v234, v66, v194 row_shr:2 row_mask:0xf bank_mask:0xf
	v_fmac_f32_dpp v235, v67, v195 row_shr:2 row_mask:0xf bank_mask:0xf
	v_fmac_f32_dpp v232, v90, v170 row_shl:15 row_mask:0xf bank_mask:0xf
; __device__ __forceinline__ unsigned cvt_pk_bf16(float lo, float hi) { unsigned r; asm("v_cvt_pk_bf16_f32 %0, %1, %2" : "=v"(r) : "v"(lo), "v"(hi)); return r; }
; __device__ __forceinline__ float sigmoid_f(float v) { return __builtin_amdgcn_rcpf(1.0f + __builtin_amdgcn_exp2f(-1.4426950409f * v)); }
; __device__ __forceinline__ u32x4 pack8(f32x4 a, f32x4 b) { u32x4 w; w.x = cvt_pk_bf16(a[0], a[1]); w.y = cvt_pk_bf16(a[2], a[3]); w.z = cvt_pk_bf16(b[0], b[1]); w.w = cvt_pk_bf16(b[2], b[3]); return w; }
; __device__ __forceinline__ f32x4 bf4(u32x2 w) { return (f32x4){bf_lo(w.x), bf_hi(w.x), bf_lo(w.y), bf_hi(w.y)}; }
;     __device__ __forceinline__ void operator()(const f32x4 (&acc)[2][2][4][2], const Unit& u, int wr, int wc, int fr, int fq) const {
;         const int row0 = u.pm * BM + wr * 64 + fr, c0 = u.pn * BM + wc * 32 + 8 * fq;
; #pragma unroll
;         for (int ai = 0; ai < 2; ++ai)
; #pragma unroll
;             for (int m = 0; m < 4; ++m) { const int row = row0 + ai * HALF + m * 16; bf16_t* rowp = UP + (size_t)row * 5632 + u.pn * HALF + wc * 32 + 8 * fq;
; #pragma unroll
;                 for (int bj = 0; bj < 2; ++bj) { const u32x4 w = pack8(acc[ai][bj][m][0], acc[ai][bj][m][1]); __builtin_nontemporal_store(w, (u32x4*)(rowp + (size_t)bj * ((size_t)16384 * 5632)));
;                     if (m == 3 && fr >= 14) *(u32x4*)(HALO + ((size_t)(row >> 6) * 2 + (fr - 14)) * 11264 + c0 + bj * HALF) = w; } }
;     }
; __device__ __forceinline__ void phase10(const Args& a, int G, int wv, bool dummy = false) {
;     ...
;             for (int t = 0; t < 8; ++t) { const f32x4 gc = bf4(gr[t]), vc = bf4(vr[t]);
;                 const f32x4 gg = wg0 * gm2 + wg1 * gm1 + wg2 * gc + bg, vv = wv0 * vm2 + wv1 * vm1 + wv2 * vc + bv;
;                 f32x4 o;
; #pragma unroll
;                 for (int e = 0; e < 4; ++e) o[e] = gg[e] * pg8::sigmoid_f(gg[e]) * vv[e];
;                 u32x2 w; w.x = cvt_pk_bf16(o[0], o[1]); w.y = cvt_pk_bf16(o[2], o[3]);
;                 if (dummy) *(u32x2*)((bf16_t*)(a.ws + WS_D) + ((((size_t)(row0 + t0 + t)) * 5632 + ch) & (size_t)0x1ffffff)) = w; else *(u32x2*)(up + (size_t)(t0 + t) * 5632) = w;
;                 gm2 = gm1; gm1 = gc; vm2 = vm1; vm1 = vc; }
	v_fmac_f32_dpp v233, v91, v171 row_shl:15 row_mask:0xf bank_mask:0xf
	v_fmac_f32_dpp v234, v78, v202 row_shl:15 row_mask:0xf bank_mask:0xf
	v_fmac_f32_dpp v235, v79, v203 row_shl:15 row_mask:0xf bank_mask:0xf
	v_fmac_f32_dpp v232, v90, v162 row_shl:14 row_mask:0xf bank_mask:0xf
	v_fmac_f32_dpp v233, v91, v163 row_shl:14 row_mask:0xf bank_mask:0xf
	v_fmac_f32_dpp v234, v78, v194 row_shl:14 row_mask:0xf bank_mask:0xf
	v_fmac_f32_dpp v235, v79, v195 row_shl:14 row_mask:0xf bank_mask:0xf
	v_mul_f32_e32 v246, v236, v232
	v_mul_f32_e32 v247, v236, v233
	v_exp_f32_e32 v246, v246
	v_exp_f32_e32 v247, v247
	s_nop 0
	v_pk_add_f32 v[246:247], v[246:247], v[238:239]
	v_rcp_f32_e32 v246, v246
	v_rcp_f32_e32 v247, v247
	v_pk_mul_f32 v[232:233], v[232:233], v[234:235]
	v_pk_mul_f32 v[232:233], v[232:233], v[246:247]
	v_cvt_pk_bf16_f32 v83, v232, v233
	v_pk_fma_f32 v[232:233], v[90:91], v[178:179], v[186:187]
	v_pk_fma_f32 v[234:235], v[78:79], v[210:211], v[218:219]
	s_nop 1
	v_fmac_f32_dpp v232, v90, v170 row_shr:1 row_mask:0xf bank_mask:0xf
	v_fmac_f32_dpp v233, v91, v171 row_shr:1 row_mask:0xf bank_mask:0xf
	v_fmac_f32_dpp v234, v78, v202 row_shr:1 row_mask:0xf bank_mask:0xf
	v_fmac_f32_dpp v235, v79, v203 row_shr:1 row_mask:0xf bank_mask:0xf
	v_fmac_f32_dpp v232, v90, v162 row_shr:2 row_mask:0xf bank_mask:0xf
	v_fmac_f32_dpp v233, v91, v163 row_shr:2 row_mask:0xf bank_mask:0xf
	v_fmac_f32_dpp v234, v78, v194 row_shr:2 row_mask:0xf bank_mask:0xf
	v_fmac_f32_dpp v235, v79, v195 row_shr:2 row_mask:0xf bank_mask:0xf
	v_fmac_f32_dpp v232, v106, v170 row_shl:15 row_mask:0xf bank_mask:0xf
	v_fmac_f32_dpp v233, v107, v171 row_shl:15 row_mask:0xf bank_mask:0xf
	v_fmac_f32_dpp v234, v94, v202 row_shl:15 row_mask:0xf bank_mask:0xf
	v_fmac_f32_dpp v235, v95, v203 row_shl:15 row_mask:0xf bank_mask:0xf
	v_fmac_f32_dpp v232, v106, v162 row_shl:14 row_mask:0xf bank_mask:0xf
	v_fmac_f32_dpp v233, v107, v163 row_shl:14 row_mask:0xf bank_mask:0xf
	v_fmac_f32_dpp v234, v94, v194 row_shl:14 row_mask:0xf bank_mask:0xf
	v_fmac_f32_dpp v235, v95, v195 row_shl:14 row_mask:0xf bank_mask:0xf
	v_mul_f32_e32 v246, v236, v232
	v_mul_f32_e32 v247, v236, v233
	v_exp_f32_e32 v246, v246
	v_exp_f32_e32 v247, v247
	s_nop 0
	v_pk_add_f32 v[246:247], v[246:247], v[238:239]
	v_rcp_f32_e32 v246, v246
	v_rcp_f32_e32 v247, v247
	v_pk_mul_f32 v[232:233], v[232:233], v[234:235]
	v_pk_mul_f32 v[232:233], v[232:233], v[246:247]
	v_cvt_pk_bf16_f32 v99, v232, v233
	v_pk_fma_f32 v[232:233], v[106:107], v[178:179], v[186:187]
	v_pk_fma_f32 v[234:235], v[94:95], v[210:211], v[218:219]
	s_nop 1
	v_fmac_f32_dpp v232, v106, v170 row_shr:1 row_mask:0xf bank_mask:0xf
	v_fmac_f32_dpp v233, v107, v171 row_shr:1 row_mask:0xf bank_mask:0xf
	v_fmac_f32_dpp v234, v94, v202 row_shr:1 row_mask:0xf bank_mask:0xf
	v_fmac_f32_dpp v235, v95, v203 row_shr:1 row_mask:0xf bank_mask:0xf
	v_fmac_f32_dpp v232, v106, v162 row_shr:2 row_mask:0xf bank_mask:0xf
	v_fmac_f32_dpp v233, v107, v163 row_shr:2 row_mask:0xf bank_mask:0xf
	v_fmac_f32_dpp v234, v94, v194 row_shr:2 row_mask:0xf bank_mask:0xf
	v_fmac_f32_dpp v235, v95, v195 row_shr:2 row_mask:0xf bank_mask:0xf
	v_fmac_f32_dpp v232, v122, v170 row_shl:15 row_mask:0xf bank_mask:0xf
	v_fmac_f32_dpp v233, v123, v171 row_shl:15 row_mask:0xf bank_mask:0xf
	v_fmac_f32_dpp v234, v110, v202 row_shl:15 row_mask:0xf bank_mask:0xf
	v_fmac_f32_dpp v235, v111, v203 row_shl:15 row_mask:0xf bank_mask:0xf
	v_fmac_f32_dpp v232, v122, v162 row_shl:14 row_mask:0xf bank_mask:0xf
	v_fmac_f32_dpp v233, v123, v163 row_shl:14 row_mask:0xf bank_mask:0xf
	v_fmac_f32_dpp v234, v110, v194 row_shl:14 row_mask:0xf bank_mask:0xf
	v_fmac_f32_dpp v235, v111, v195 row_shl:14 row_mask:0xf bank_mask:0xf
	v_mul_f32_e32 v246, v236, v232
	v_mul_f32_e32 v247, v236, v233
	v_exp_f32_e32 v246, v246
	v_exp_f32_e32 v247, v247
	s_nop 0
	v_pk_add_f32 v[246:247], v[246:247], v[238:239]
	v_rcp_f32_e32 v246, v246
	v_rcp_f32_e32 v247, v247
	v_pk_mul_f32 v[232:233], v[232:233], v[234:235]
	v_pk_mul_f32 v[232:233], v[232:233], v[246:247]
	v_cvt_pk_bf16_f32 v115, v232, v233
	v_pk_fma_f32 v[232:233], v[122:123], v[178:179], v[186:187]
	v_pk_fma_f32 v[234:235], v[110:111], v[210:211], v[218:219]
	s_nop 1
	v_fmac_f32_dpp v232, v122, v170 row_shr:1 row_mask:0xf bank_mask:0xf
	v_fmac_f32_dpp v233, v123, v171 row_shr:1 row_mask:0xf bank_mask:0xf
	v_fmac_f32_dpp v234, v110, v202 row_shr:1 row_mask:0xf bank_mask:0xf
	v_fmac_f32_dpp v235, v111, v203 row_shr:1 row_mask:0xf bank_mask:0xf
	v_fmac_f32_dpp v232, v122, v162 row_shr:2 row_mask:0xf bank_mask:0xf
	v_fmac_f32_dpp v233, v123, v163 row_shr:2 row_mask:0xf bank_mask:0xf
	v_fmac_f32_dpp v234, v110, v194 row_shr:2 row_mask:0xf bank_mask:0xf
	v_fmac_f32_dpp v235, v111, v195 row_shr:2 row_mask:0xf bank_mask:0xf
	v_mul_f32_e32 v246, v236, v232
	v_mul_f32_e32 v247, v236, v233
	v_exp_f32_e32 v246, v246
	v_exp_f32_e32 v247, v247
	s_nop 0
	v_pk_add_f32 v[246:247], v[246:247], v[238:239]
	v_rcp_f32_e32 v246, v246
	v_rcp_f32_e32 v247, v247
	v_pk_mul_f32 v[232:233], v[232:233], v[234:235]
	v_pk_mul_f32 v[232:233], v[232:233], v[246:247]
	v_cvt_pk_bf16_f32 v127, v232, v233
	s_andn2_b64 exec, exec, s[64:65]
	global_store_dwordx4 v149, v[124:127], s[100:101]
	s_mov_b64 exec, -1
	s_add_u32 s36, s100, 0x2c000
	s_addc_u32 s37, s101, 0
	global_store_dwordx4 v149, v[112:115], s[36:37]
	s_add_u32 s36, s100, 0x58000
	s_addc_u32 s37, s101, 0
	global_store_dwordx4 v149, v[96:99], s[36:37]
	s_add_u32 s36, s100, 0x84000
	s_addc_u32 s37, s101, 0
	global_store_dwordx4 v149, v[80:83], s[36:37]
	s_nop 4
	v_pk_fma_f32 v[232:233], v[16:17], v[172:173], v[180:181]
	v_pk_fma_f32 v[234:235], v[4:5], v[204:205], v[212:213]
; __device__ __forceinline__ unsigned cvt_pk_bf16(float lo, float hi) { unsigned r; asm("v_cvt_pk_bf16_f32 %0, %1, %2" : "=v"(r) : "v"(lo), "v"(hi)); return r; }
; __device__ __forceinline__ float sigmoid_f(float v) { return __builtin_amdgcn_rcpf(1.0f + __builtin_amdgcn_exp2f(-1.4426950409f * v)); }
; __device__ __forceinline__ u32x4 pack8(f32x4 a, f32x4 b) { u32x4 w; w.x = cvt_pk_bf16(a[0], a[1]); w.y = cvt_pk_bf16(a[2], a[3]); w.z = cvt_pk_bf16(b[0], b[1]); w.w = cvt_pk_bf16(b[2], b[3]); return w; }
; __device__ __forceinline__ f32x4 bf4(u32x2 w) { return (f32x4){bf_lo(w.x), bf_hi(w.x), bf_lo(w.y), bf_hi(w.y)}; }
;     __device__ __forceinline__ void operator()(const f32x4 (&acc)[2][2][4][2], const Unit& u, int wr, int wc, int fr, int fq) const {
;         const int row0 = u.pm * BM + wr * 64 + fr, c0 = u.pn * BM + wc * 32 + 8 * fq;
; #pragma unroll
;         for (int ai = 0; ai < 2; ++ai)
; #pragma unroll
;             for (int m = 0; m < 4; ++m) { const int row = row0 + ai * HALF + m * 16; bf16_t* rowp = UP + (size_t)row * 5632 + u.pn * HALF + wc * 32 + 8 * fq;
; #pragma unroll
;                 for (int bj = 0; bj < 2; ++bj) { const u32x4 w = pack8(acc[ai][bj][m][0], acc[ai][bj][m][1]); __builtin_nontemporal_store(w, (u32x4*)(rowp + (size_t)bj * ((size_t)16384 * 5632)));
;                     if (m == 3 && fr >= 14) *(u32x4*)(HALO + ((size_t)(row >> 6) * 2 + (fr - 14)) * 11264 + c0 + bj * HALF) = w; } }
;     }
; __device__ __forceinline__ void phase10(const Args& a, int G, int wv, bool dummy = false) {
;     ...
;             for (int t = 0; t < 8; ++t) { const f32x4 gc = bf4(gr[t]), vc = bf4(vr[t]);
;                 const f32x4 gg = wg0 * gm2 + wg1 * gm1 + wg2 * gc + bg, vv = wv0 * vm2 + wv1 * vm1 + wv2 * vc + bv;
;                 f32x4 o;
; #pragma unroll
;                 for (int e = 0; e < 4; ++e) o[e] = gg[e] * pg8::sigmoid_f(gg[e]) * vv[e];
;                 u32x2 w; w.x = cvt_pk_bf16(o[0], o[1]); w.y = cvt_pk_bf16(o[2], o[3]);
;                 if (dummy) *(u32x2*)((bf16_t*)(a.ws + WS_D) + ((((size_t)(row0 + t0 + t)) * 5632 + ch) & (size_t)0x1ffffff)) = w; else *(u32x2*)(up + (size_t)(t0 + t) * 5632) = w;
;                 gm2 = gm1; gm1 = gc; vm2 = vm1; vm1 = vc; }
	s_nop 1
	v_fmac_f32_dpp v232, v16, v164 row_shr:1 row_mask:0xf bank_mask:0xf
	v_fmac_f32_dpp v233, v17, v165 row_shr:1 row_mask:0xf bank_mask:0xf
	v_fmac_f32_dpp v234, v4, v196 row_shr:1 row_mask:0xf bank_mask:0xf
	v_fmac_f32_dpp v235, v5, v197 row_shr:1 row_mask:0xf bank_mask:0xf
	v_fmac_f32_dpp v232, v16, v156 row_shr:2 row_mask:0xf bank_mask:0xf
	v_fmac_f32_dpp v233, v17, v157 row_shr:2 row_mask:0xf bank_mask:0xf
	v_fmac_f32_dpp v234, v4, v188 row_shr:2 row_mask:0xf bank_mask:0xf
	v_fmac_f32_dpp v235, v5, v189 row_shr:2 row_mask:0xf bank_mask:0xf
	v_fmac_f32_dpp v232, v32, v164 row_shl:15 row_mask:0xf bank_mask:0xf
	v_fmac_f32_dpp v233, v33, v165 row_shl:15 row_mask:0xf bank_mask:0xf
	v_fmac_f32_dpp v234, v20, v196 row_shl:15 row_mask:0xf bank_mask:0xf
	v_fmac_f32_dpp v235, v21, v197 row_shl:15 row_mask:0xf bank_mask:0xf
	v_fmac_f32_dpp v232, v32, v156 row_shl:14 row_mask:0xf bank_mask:0xf
	v_fmac_f32_dpp v233, v33, v157 row_shl:14 row_mask:0xf bank_mask:0xf
	v_fmac_f32_dpp v234, v20, v188 row_shl:14 row_mask:0xf bank_mask:0xf
	v_fmac_f32_dpp v235, v21, v189 row_shl:14 row_mask:0xf bank_mask:0xf
	v_mul_f32_e32 v246, v236, v232
	v_mul_f32_e32 v247, v236, v233
	v_exp_f32_e32 v246, v246
	v_exp_f32_e32 v247, v247
	s_nop 0
	v_pk_add_f32 v[246:247], v[246:247], v[238:239]
	v_rcp_f32_e32 v246, v246
	v_rcp_f32_e32 v247, v247
	v_pk_mul_f32 v[232:233], v[232:233], v[234:235]
	v_pk_mul_f32 v[232:233], v[232:233], v[246:247]
	v_cvt_pk_bf16_f32 v16, v232, v233
	v_pk_fma_f32 v[232:233], v[32:33], v[172:173], v[180:181]
	v_pk_fma_f32 v[234:235], v[20:21], v[204:205], v[212:213]
	s_nop 1
	v_fmac_f32_dpp v232, v32, v164 row_shr:1 row_mask:0xf bank_mask:0xf
	v_fmac_f32_dpp v233, v33, v165 row_shr:1 row_mask:0xf bank_mask:0xf
	v_fmac_f32_dpp v234, v20, v196 row_shr:1 row_mask:0xf bank_mask:0xf
	v_fmac_f32_dpp v235, v21, v197 row_shr:1 row_mask:0xf bank_mask:0xf
	v_fmac_f32_dpp v232, v32, v156 row_shr:2 row_mask:0xf bank_mask:0xf
	v_fmac_f32_dpp v233, v33, v157 row_shr:2 row_mask:0xf bank_mask:0xf
	v_fmac_f32_dpp v234, v20, v188 row_shr:2 row_mask:0xf bank_mask:0xf
	v_fmac_f32_dpp v235, v21, v189 row_shr:2 row_mask:0xf bank_mask:0xf
	v_fmac_f32_dpp v232, v48, v164 row_shl:15 row_mask:0xf bank_mask:0xf
	v_fmac_f32_dpp v233, v49, v165 row_shl:15 row_mask:0xf bank_mask:0xf
	v_fmac_f32_dpp v234, v36, v196 row_shl:15 row_mask:0xf bank_mask:0xf
	v_fmac_f32_dpp v235, v37, v197 row_shl:15 row_mask:0xf bank_mask:0xf
	v_fmac_f32_dpp v232, v48, v156 row_shl:14 row_mask:0xf bank_mask:0xf
	v_fmac_f32_dpp v233, v49, v157 row_shl:14 row_mask:0xf bank_mask:0xf
	v_fmac_f32_dpp v234, v36, v188 row_shl:14 row_mask:0xf bank_mask:0xf
	v_fmac_f32_dpp v235, v37, v189 row_shl:14 row_mask:0xf bank_mask:0xf
	v_mul_f32_e32 v246, v236, v232
	v_mul_f32_e32 v247, v236, v233
	v_exp_f32_e32 v246, v246
	v_exp_f32_e32 v247, v247
	s_nop 0
	v_pk_add_f32 v[246:247], v[246:247], v[238:239]
	v_rcp_f32_e32 v246, v246
	v_rcp_f32_e32 v247, v247
	v_pk_mul_f32 v[232:233], v[232:233], v[234:235]
	v_pk_mul_f32 v[232:233], v[232:233], v[246:247]
	v_cvt_pk_bf16_f32 v32, v232, v233
	v_pk_fma_f32 v[232:233], v[48:49], v[172:173], v[180:181]
	v_pk_fma_f32 v[234:235], v[36:37], v[204:205], v[212:213]
	s_nop 1
	v_fmac_f32_dpp v232, v48, v164 row_shr:1 row_mask:0xf bank_mask:0xf
	v_fmac_f32_dpp v233, v49, v165 row_shr:1 row_mask:0xf bank_mask:0xf
	v_fmac_f32_dpp v234, v36, v196 row_shr:1 row_mask:0xf bank_mask:0xf
	v_fmac_f32_dpp v235, v37, v197 row_shr:1 row_mask:0xf bank_mask:0xf
	v_fmac_f32_dpp v232, v48, v156 row_shr:2 row_mask:0xf bank_mask:0xf
	v_fmac_f32_dpp v233, v49, v157 row_shr:2 row_mask:0xf bank_mask:0xf
	v_fmac_f32_dpp v234, v36, v188 row_shr:2 row_mask:0xf bank_mask:0xf
	v_fmac_f32_dpp v235, v37, v189 row_shr:2 row_mask:0xf bank_mask:0xf
	v_fmac_f32_dpp v232, v60, v164 row_shl:15 row_mask:0xf bank_mask:0xf
	v_fmac_f32_dpp v233, v61, v165 row_shl:15 row_mask:0xf bank_mask:0xf
	v_fmac_f32_dpp v234, v52, v196 row_shl:15 row_mask:0xf bank_mask:0xf
	v_fmac_f32_dpp v235, v53, v197 row_shl:15 row_mask:0xf bank_mask:0xf
	v_fmac_f32_dpp v232, v60, v156 row_shl:14 row_mask:0xf bank_mask:0xf
	v_fmac_f32_dpp v233, v61, v157 row_shl:14 row_mask:0xf bank_mask:0xf
	v_fmac_f32_dpp v234, v52, v188 row_shl:14 row_mask:0xf bank_mask:0xf
	v_fmac_f32_dpp v235, v53, v189 row_shl:14 row_mask:0xf bank_mask:0xf
	v_mul_f32_e32 v246, v236, v232
	v_mul_f32_e32 v247, v236, v233
	v_exp_f32_e32 v246, v246
	v_exp_f32_e32 v247, v247
	s_nop 0
	v_pk_add_f32 v[246:247], v[246:247], v[238:239]
	v_rcp_f32_e32 v246, v246
	v_rcp_f32_e32 v247, v247
	v_pk_mul_f32 v[232:233], v[232:233], v[234:235]
	v_pk_mul_f32 v[232:233], v[232:233], v[246:247]
	v_cvt_pk_bf16_f32 v48, v232, v233
	v_pk_fma_f32 v[232:233], v[60:61], v[172:173], v[180:181]
	v_pk_fma_f32 v[234:235], v[52:53], v[204:205], v[212:213]
	s_nop 1
	v_fmac_f32_dpp v232, v60, v164 row_shr:1 row_mask:0xf bank_mask:0xf
	v_fmac_f32_dpp v233, v61, v165 row_shr:1 row_mask:0xf bank_mask:0xf
	v_fmac_f32_dpp v234, v52, v196 row_shr:1 row_mask:0xf bank_mask:0xf
	v_fmac_f32_dpp v235, v53, v197 row_shr:1 row_mask:0xf bank_mask:0xf
	v_fmac_f32_dpp v232, v60, v156 row_shr:2 row_mask:0xf bank_mask:0xf
	v_fmac_f32_dpp v233, v61, v157 row_shr:2 row_mask:0xf bank_mask:0xf
	v_fmac_f32_dpp v234, v52, v188 row_shr:2 row_mask:0xf bank_mask:0xf
	v_fmac_f32_dpp v235, v53, v189 row_shr:2 row_mask:0xf bank_mask:0xf
	v_mul_f32_e32 v246, v236, v232
	v_mul_f32_e32 v247, v236, v233
	v_exp_f32_e32 v246, v246
	v_exp_f32_e32 v247, v247
	s_nop 0
	v_pk_add_f32 v[246:247], v[246:247], v[238:239]
	v_rcp_f32_e32 v246, v246
	v_rcp_f32_e32 v247, v247
	v_pk_mul_f32 v[232:233], v[232:233], v[234:235]
; __device__ __forceinline__ unsigned cvt_pk_bf16(float lo, float hi) { unsigned r; asm("v_cvt_pk_bf16_f32 %0, %1, %2" : "=v"(r) : "v"(lo), "v"(hi)); return r; }
; __device__ __forceinline__ float sigmoid_f(float v) { return __builtin_amdgcn_rcpf(1.0f + __builtin_amdgcn_exp2f(-1.4426950409f * v)); }
; __device__ __forceinline__ u32x4 pack8(f32x4 a, f32x4 b) { u32x4 w; w.x = cvt_pk_bf16(a[0], a[1]); w.y = cvt_pk_bf16(a[2], a[3]); w.z = cvt_pk_bf16(b[0], b[1]); w.w = cvt_pk_bf16(b[2], b[3]); return w; }
; __device__ __forceinline__ f32x4 bf4(u32x2 w) { return (f32x4){bf_lo(w.x), bf_hi(w.x), bf_lo(w.y), bf_hi(w.y)}; }
;     __device__ __forceinline__ void operator()(const f32x4 (&acc)[2][2][4][2], const Unit& u, int wr, int wc, int fr, int fq) const {
;         const int row0 = u.pm * BM + wr * 64 + fr, c0 = u.pn * BM + wc * 32 + 8 * fq;
; #pragma unroll
;         for (int ai = 0; ai < 2; ++ai)
; #pragma unroll
;             for (int m = 0; m < 4; ++m) { const int row = row0 + ai * HALF + m * 16; bf16_t* rowp = UP + (size_t)row * 5632 + u.pn * HALF + wc * 32 + 8 * fq;
; #pragma unroll
;                 for (int bj = 0; bj < 2; ++bj) { const u32x4 w = pack8(acc[ai][bj][m][0], acc[ai][bj][m][1]); __builtin_nontemporal_store(w, (u32x4*)(rowp + (size_t)bj * ((size_t)16384 * 5632)));
;                     if (m == 3 && fr >= 14) *(u32x4*)(HALO + ((size_t)(row >> 6) * 2 + (fr - 14)) * 11264 + c0 + bj * HALF) = w; } }
;     }
; __device__ __forceinline__ void phase10(const Args& a, int G, int wv, bool dummy = false) {
;     ...
;             for (int t = 0; t < 8; ++t) { const f32x4 gc = bf4(gr[t]), vc = bf4(vr[t]);
;                 const f32x4 gg = wg0 * gm2 + wg1 * gm1 + wg2 * gc + bg, vv = wv0 * vm2 + wv1 * vm1 + wv2 * vc + bv;
;                 f32x4 o;
; #pragma unroll
;                 for (int e = 0; e < 4; ++e) o[e] = gg[e] * pg8::sigmoid_f(gg[e]) * vv[e];
;                 u32x2 w; w.x = cvt_pk_bf16(o[0], o[1]); w.y = cvt_pk_bf16(o[2], o[3]);
;                 if (dummy) *(u32x2*)((bf16_t*)(a.ws + WS_D) + ((((size_t)(row0 + t0 + t)) * 5632 + ch) & (size_t)0x1ffffff)) = w; else *(u32x2*)(up + (size_t)(t0 + t) * 5632) = w;
;                 gm2 = gm1; gm1 = gc; vm2 = vm1; vm1 = vc; }
	v_pk_mul_f32 v[232:233], v[232:233], v[246:247]
	v_cvt_pk_bf16_f32 v60, v232, v233
	v_pk_fma_f32 v[232:233], v[18:19], v[174:175], v[182:183]
	v_pk_fma_f32 v[234:235], v[6:7], v[206:207], v[214:215]
	s_nop 1
	v_fmac_f32_dpp v232, v18, v166 row_shr:1 row_mask:0xf bank_mask:0xf
	v_fmac_f32_dpp v233, v19, v167 row_shr:1 row_mask:0xf bank_mask:0xf
	v_fmac_f32_dpp v234, v6, v198 row_shr:1 row_mask:0xf bank_mask:0xf
	v_fmac_f32_dpp v235, v7, v199 row_shr:1 row_mask:0xf bank_mask:0xf
	v_fmac_f32_dpp v232, v18, v158 row_shr:2 row_mask:0xf bank_mask:0xf
	v_fmac_f32_dpp v233, v19, v159 row_shr:2 row_mask:0xf bank_mask:0xf
	v_fmac_f32_dpp v234, v6, v190 row_shr:2 row_mask:0xf bank_mask:0xf
	v_fmac_f32_dpp v235, v7, v191 row_shr:2 row_mask:0xf bank_mask:0xf
	v_fmac_f32_dpp v232, v34, v166 row_shl:15 row_mask:0xf bank_mask:0xf
	v_fmac_f32_dpp v233, v35, v167 row_shl:15 row_mask:0xf bank_mask:0xf
	v_fmac_f32_dpp v234, v22, v198 row_shl:15 row_mask:0xf bank_mask:0xf
	v_fmac_f32_dpp v235, v23, v199 row_shl:15 row_mask:0xf bank_mask:0xf
	v_fmac_f32_dpp v232, v34, v158 row_shl:14 row_mask:0xf bank_mask:0xf
	v_fmac_f32_dpp v233, v35, v159 row_shl:14 row_mask:0xf bank_mask:0xf
	v_fmac_f32_dpp v234, v22, v190 row_shl:14 row_mask:0xf bank_mask:0xf
	v_fmac_f32_dpp v235, v23, v191 row_shl:14 row_mask:0xf bank_mask:0xf
	v_mul_f32_e32 v246, v236, v232
	v_mul_f32_e32 v247, v236, v233
	v_exp_f32_e32 v246, v246
	v_exp_f32_e32 v247, v247
	s_nop 0
	v_pk_add_f32 v[246:247], v[246:247], v[238:239]
	v_rcp_f32_e32 v246, v246
	v_rcp_f32_e32 v247, v247
	v_pk_mul_f32 v[232:233], v[232:233], v[234:235]
	v_pk_mul_f32 v[232:233], v[232:233], v[246:247]
	v_cvt_pk_bf16_f32 v17, v232, v233
	v_pk_fma_f32 v[232:233], v[34:35], v[174:175], v[182:183]
	v_pk_fma_f32 v[234:235], v[22:23], v[206:207], v[214:215]
	s_nop 1
	v_fmac_f32_dpp v232, v34, v166 row_shr:1 row_mask:0xf bank_mask:0xf
	v_fmac_f32_dpp v233, v35, v167 row_shr:1 row_mask:0xf bank_mask:0xf
	v_fmac_f32_dpp v234, v22, v198 row_shr:1 row_mask:0xf bank_mask:0xf
	v_fmac_f32_dpp v235, v23, v199 row_shr:1 row_mask:0xf bank_mask:0xf
	v_fmac_f32_dpp v232, v34, v158 row_shr:2 row_mask:0xf bank_mask:0xf
	v_fmac_f32_dpp v233, v35, v159 row_shr:2 row_mask:0xf bank_mask:0xf
	v_fmac_f32_dpp v234, v22, v190 row_shr:2 row_mask:0xf bank_mask:0xf
	v_fmac_f32_dpp v235, v23, v191 row_shr:2 row_mask:0xf bank_mask:0xf
	v_fmac_f32_dpp v232, v50, v166 row_shl:15 row_mask:0xf bank_mask:0xf
	v_fmac_f32_dpp v233, v51, v167 row_shl:15 row_mask:0xf bank_mask:0xf
	v_fmac_f32_dpp v234, v38, v198 row_shl:15 row_mask:0xf bank_mask:0xf
	v_fmac_f32_dpp v235, v39, v199 row_shl:15 row_mask:0xf bank_mask:0xf
	v_fmac_f32_dpp v232, v50, v158 row_shl:14 row_mask:0xf bank_mask:0xf
	v_fmac_f32_dpp v233, v51, v159 row_shl:14 row_mask:0xf bank_mask:0xf
	v_fmac_f32_dpp v234, v38, v190 row_shl:14 row_mask:0xf bank_mask:0xf
	v_fmac_f32_dpp v235, v39, v191 row_shl:14 row_mask:0xf bank_mask:0xf
	v_mul_f32_e32 v246, v236, v232
	v_mul_f32_e32 v247, v236, v233
	v_exp_f32_e32 v246, v246
	v_exp_f32_e32 v247, v247
	s_nop 0
	v_pk_add_f32 v[246:247], v[246:247], v[238:239]
	v_rcp_f32_e32 v246, v246
	v_rcp_f32_e32 v247, v247
	v_pk_mul_f32 v[232:233], v[232:233], v[234:235]
	v_pk_mul_f32 v[232:233], v[232:233], v[246:247]
	v_cvt_pk_bf16_f32 v33, v232, v233
	v_pk_fma_f32 v[232:233], v[50:51], v[174:175], v[182:183]
	v_pk_fma_f32 v[234:235], v[38:39], v[206:207], v[214:215]
	s_nop 1
	v_fmac_f32_dpp v232, v50, v166 row_shr:1 row_mask:0xf bank_mask:0xf
	v_fmac_f32_dpp v233, v51, v167 row_shr:1 row_mask:0xf bank_mask:0xf
	v_fmac_f32_dpp v234, v38, v198 row_shr:1 row_mask:0xf bank_mask:0xf
	v_fmac_f32_dpp v235, v39, v199 row_shr:1 row_mask:0xf bank_mask:0xf
	v_fmac_f32_dpp v232, v50, v158 row_shr:2 row_mask:0xf bank_mask:0xf
	v_fmac_f32_dpp v233, v51, v159 row_shr:2 row_mask:0xf bank_mask:0xf
	v_fmac_f32_dpp v234, v38, v190 row_shr:2 row_mask:0xf bank_mask:0xf
	v_fmac_f32_dpp v235, v39, v191 row_shr:2 row_mask:0xf bank_mask:0xf
	v_fmac_f32_dpp v232, v62, v166 row_shl:15 row_mask:0xf bank_mask:0xf
	v_fmac_f32_dpp v233, v63, v167 row_shl:15 row_mask:0xf bank_mask:0xf
	v_fmac_f32_dpp v234, v54, v198 row_shl:15 row_mask:0xf bank_mask:0xf
	v_fmac_f32_dpp v235, v55, v199 row_shl:15 row_mask:0xf bank_mask:0xf
	v_fmac_f32_dpp v232, v62, v158 row_shl:14 row_mask:0xf bank_mask:0xf
	v_fmac_f32_dpp v233, v63, v159 row_shl:14 row_mask:0xf bank_mask:0xf
	v_fmac_f32_dpp v234, v54, v190 row_shl:14 row_mask:0xf bank_mask:0xf
	v_fmac_f32_dpp v235, v55, v191 row_shl:14 row_mask:0xf bank_mask:0xf
	v_mul_f32_e32 v246, v236, v232
	v_mul_f32_e32 v247, v236, v233
	v_exp_f32_e32 v246, v246
	v_exp_f32_e32 v247, v247
	s_nop 0
	v_pk_add_f32 v[246:247], v[246:247], v[238:239]
	v_rcp_f32_e32 v246, v246
	v_rcp_f32_e32 v247, v247
	v_pk_mul_f32 v[232:233], v[232:233], v[234:235]
	v_pk_mul_f32 v[232:233], v[232:233], v[246:247]
	v_cvt_pk_bf16_f32 v49, v232, v233
	v_pk_fma_f32 v[232:233], v[62:63], v[174:175], v[182:183]
	v_pk_fma_f32 v[234:235], v[54:55], v[206:207], v[214:215]
	s_nop 1
	v_fmac_f32_dpp v232, v62, v166 row_shr:1 row_mask:0xf bank_mask:0xf
	v_fmac_f32_dpp v233, v63, v167 row_shr:1 row_mask:0xf bank_mask:0xf
	v_fmac_f32_dpp v234, v54, v198 row_shr:1 row_mask:0xf bank_mask:0xf
	v_fmac_f32_dpp v235, v55, v199 row_shr:1 row_mask:0xf bank_mask:0xf
	v_fmac_f32_dpp v232, v62, v158 row_shr:2 row_mask:0xf bank_mask:0xf
	v_fmac_f32_dpp v233, v63, v159 row_shr:2 row_mask:0xf bank_mask:0xf
	v_fmac_f32_dpp v234, v54, v190 row_shr:2 row_mask:0xf bank_mask:0xf
	v_fmac_f32_dpp v235, v55, v191 row_shr:2 row_mask:0xf bank_mask:0xf
	v_mul_f32_e32 v246, v236, v232
	v_mul_f32_e32 v247, v236, v233
	v_exp_f32_e32 v246, v246
; __device__ __forceinline__ unsigned cvt_pk_bf16(float lo, float hi) { unsigned r; asm("v_cvt_pk_bf16_f32 %0, %1, %2" : "=v"(r) : "v"(lo), "v"(hi)); return r; }
; __device__ __forceinline__ float sigmoid_f(float v) { return __builtin_amdgcn_rcpf(1.0f + __builtin_amdgcn_exp2f(-1.4426950409f * v)); }
; __device__ __forceinline__ u32x4 pack8(f32x4 a, f32x4 b) { u32x4 w; w.x = cvt_pk_bf16(a[0], a[1]); w.y = cvt_pk_bf16(a[2], a[3]); w.z = cvt_pk_bf16(b[0], b[1]); w.w = cvt_pk_bf16(b[2], b[3]); return w; }
; __device__ __forceinline__ f32x4 bf4(u32x2 w) { return (f32x4){bf_lo(w.x), bf_hi(w.x), bf_lo(w.y), bf_hi(w.y)}; }
;     __device__ __forceinline__ void operator()(const f32x4 (&acc)[2][2][4][2], const Unit& u, int wr, int wc, int fr, int fq) const {
;         const int row0 = u.pm * BM + wr * 64 + fr, c0 = u.pn * BM + wc * 32 + 8 * fq;
; #pragma unroll
;         for (int ai = 0; ai < 2; ++ai)
; #pragma unroll
;             for (int m = 0; m < 4; ++m) { const int row = row0 + ai * HALF + m * 16; bf16_t* rowp = UP + (size_t)row * 5632 + u.pn * HALF + wc * 32 + 8 * fq;
; #pragma unroll
;                 for (int bj = 0; bj < 2; ++bj) { const u32x4 w = pack8(acc[ai][bj][m][0], acc[ai][bj][m][1]); __builtin_nontemporal_store(w, (u32x4*)(rowp + (size_t)bj * ((size_t)16384 * 5632)));
;                     if (m == 3 && fr >= 14) *(u32x4*)(HALO + ((size_t)(row >> 6) * 2 + (fr - 14)) * 11264 + c0 + bj * HALF) = w; } }
;     }
; __device__ __forceinline__ void phase10(const Args& a, int G, int wv, bool dummy = false) {
;     ...
;             for (int t = 0; t < 8; ++t) { const f32x4 gc = bf4(gr[t]), vc = bf4(vr[t]);
;                 const f32x4 gg = wg0 * gm2 + wg1 * gm1 + wg2 * gc + bg, vv = wv0 * vm2 + wv1 * vm1 + wv2 * vc + bv;
;                 f32x4 o;
; #pragma unroll
;                 for (int e = 0; e < 4; ++e) o[e] = gg[e] * pg8::sigmoid_f(gg[e]) * vv[e];
;                 u32x2 w; w.x = cvt_pk_bf16(o[0], o[1]); w.y = cvt_pk_bf16(o[2], o[3]);
;                 if (dummy) *(u32x2*)((bf16_t*)(a.ws + WS_D) + ((((size_t)(row0 + t0 + t)) * 5632 + ch) & (size_t)0x1ffffff)) = w; else *(u32x2*)(up + (size_t)(t0 + t) * 5632) = w;
;                 gm2 = gm1; gm1 = gc; vm2 = vm1; vm1 = vc; }
	v_exp_f32_e32 v247, v247
	s_nop 0
	v_pk_add_f32 v[246:247], v[246:247], v[238:239]
	v_rcp_f32_e32 v246, v246
	v_rcp_f32_e32 v247, v247
	v_pk_mul_f32 v[232:233], v[232:233], v[234:235]
	v_pk_mul_f32 v[232:233], v[232:233], v[246:247]
	v_cvt_pk_bf16_f32 v61, v232, v233
	v_pk_fma_f32 v[232:233], v[8:9], v[176:177], v[184:185]
	v_pk_fma_f32 v[234:235], v[0:1], v[208:209], v[216:217]
	s_nop 1
	v_fmac_f32_dpp v232, v8, v168 row_shr:1 row_mask:0xf bank_mask:0xf
	v_fmac_f32_dpp v233, v9, v169 row_shr:1 row_mask:0xf bank_mask:0xf
	v_fmac_f32_dpp v234, v0, v200 row_shr:1 row_mask:0xf bank_mask:0xf
	v_fmac_f32_dpp v235, v1, v201 row_shr:1 row_mask:0xf bank_mask:0xf
	v_fmac_f32_dpp v232, v8, v160 row_shr:2 row_mask:0xf bank_mask:0xf
	v_fmac_f32_dpp v233, v9, v161 row_shr:2 row_mask:0xf bank_mask:0xf
	v_fmac_f32_dpp v234, v0, v192 row_shr:2 row_mask:0xf bank_mask:0xf
	v_fmac_f32_dpp v235, v1, v193 row_shr:2 row_mask:0xf bank_mask:0xf
	v_fmac_f32_dpp v232, v24, v168 row_shl:15 row_mask:0xf bank_mask:0xf
	v_fmac_f32_dpp v233, v25, v169 row_shl:15 row_mask:0xf bank_mask:0xf
	v_fmac_f32_dpp v234, v12, v200 row_shl:15 row_mask:0xf bank_mask:0xf
	v_fmac_f32_dpp v235, v13, v201 row_shl:15 row_mask:0xf bank_mask:0xf
	v_fmac_f32_dpp v232, v24, v160 row_shl:14 row_mask:0xf bank_mask:0xf
	v_fmac_f32_dpp v233, v25, v161 row_shl:14 row_mask:0xf bank_mask:0xf
	v_fmac_f32_dpp v234, v12, v192 row_shl:14 row_mask:0xf bank_mask:0xf
	v_fmac_f32_dpp v235, v13, v193 row_shl:14 row_mask:0xf bank_mask:0xf
	v_mul_f32_e32 v246, v236, v232
	v_mul_f32_e32 v247, v236, v233
	v_exp_f32_e32 v246, v246
	v_exp_f32_e32 v247, v247
	s_nop 0
	v_pk_add_f32 v[246:247], v[246:247], v[238:239]
	v_rcp_f32_e32 v246, v246
	v_rcp_f32_e32 v247, v247
	v_pk_mul_f32 v[232:233], v[232:233], v[234:235]
	v_pk_mul_f32 v[232:233], v[232:233], v[246:247]
	v_cvt_pk_bf16_f32 v18, v232, v233
	v_pk_fma_f32 v[232:233], v[24:25], v[176:177], v[184:185]
	v_pk_fma_f32 v[234:235], v[12:13], v[208:209], v[216:217]
	s_nop 1
	v_fmac_f32_dpp v232, v24, v168 row_shr:1 row_mask:0xf bank_mask:0xf
	v_fmac_f32_dpp v233, v25, v169 row_shr:1 row_mask:0xf bank_mask:0xf
	v_fmac_f32_dpp v234, v12, v200 row_shr:1 row_mask:0xf bank_mask:0xf
	v_fmac_f32_dpp v235, v13, v201 row_shr:1 row_mask:0xf bank_mask:0xf
	v_fmac_f32_dpp v232, v24, v160 row_shr:2 row_mask:0xf bank_mask:0xf
	v_fmac_f32_dpp v233, v25, v161 row_shr:2 row_mask:0xf bank_mask:0xf
	v_fmac_f32_dpp v234, v12, v192 row_shr:2 row_mask:0xf bank_mask:0xf
	v_fmac_f32_dpp v235, v13, v193 row_shr:2 row_mask:0xf bank_mask:0xf
	v_fmac_f32_dpp v232, v40, v168 row_shl:15 row_mask:0xf bank_mask:0xf
	v_fmac_f32_dpp v233, v41, v169 row_shl:15 row_mask:0xf bank_mask:0xf
	v_fmac_f32_dpp v234, v28, v200 row_shl:15 row_mask:0xf bank_mask:0xf
	v_fmac_f32_dpp v235, v29, v201 row_shl:15 row_mask:0xf bank_mask:0xf
	v_fmac_f32_dpp v232, v40, v160 row_shl:14 row_mask:0xf bank_mask:0xf
	v_fmac_f32_dpp v233, v41, v161 row_shl:14 row_mask:0xf bank_mask:0xf
	v_fmac_f32_dpp v234, v28, v192 row_shl:14 row_mask:0xf bank_mask:0xf
	v_fmac_f32_dpp v235, v29, v193 row_shl:14 row_mask:0xf bank_mask:0xf
	v_mul_f32_e32 v246, v236, v232
	v_mul_f32_e32 v247, v236, v233
	v_exp_f32_e32 v246, v246
	v_exp_f32_e32 v247, v247
	s_nop 0
	v_pk_add_f32 v[246:247], v[246:247], v[238:239]
	v_rcp_f32_e32 v246, v246
	v_rcp_f32_e32 v247, v247
	v_pk_mul_f32 v[232:233], v[232:233], v[234:235]
	v_pk_mul_f32 v[232:233], v[232:233], v[246:247]
	v_cvt_pk_bf16_f32 v34, v232, v233
	v_pk_fma_f32 v[232:233], v[40:41], v[176:177], v[184:185]
	v_pk_fma_f32 v[234:235], v[28:29], v[208:209], v[216:217]
	s_nop 1
	v_fmac_f32_dpp v232, v40, v168 row_shr:1 row_mask:0xf bank_mask:0xf
	v_fmac_f32_dpp v233, v41, v169 row_shr:1 row_mask:0xf bank_mask:0xf
	v_fmac_f32_dpp v234, v28, v200 row_shr:1 row_mask:0xf bank_mask:0xf
	v_fmac_f32_dpp v235, v29, v201 row_shr:1 row_mask:0xf bank_mask:0xf
	v_fmac_f32_dpp v232, v40, v160 row_shr:2 row_mask:0xf bank_mask:0xf
	v_fmac_f32_dpp v233, v41, v161 row_shr:2 row_mask:0xf bank_mask:0xf
	v_fmac_f32_dpp v234, v28, v192 row_shr:2 row_mask:0xf bank_mask:0xf
	v_fmac_f32_dpp v235, v29, v193 row_shr:2 row_mask:0xf bank_mask:0xf
	v_fmac_f32_dpp v232, v56, v168 row_shl:15 row_mask:0xf bank_mask:0xf
	v_fmac_f32_dpp v233, v57, v169 row_shl:15 row_mask:0xf bank_mask:0xf
	v_fmac_f32_dpp v234, v44, v200 row_shl:15 row_mask:0xf bank_mask:0xf
	v_fmac_f32_dpp v235, v45, v201 row_shl:15 row_mask:0xf bank_mask:0xf
	v_fmac_f32_dpp v232, v56, v160 row_shl:14 row_mask:0xf bank_mask:0xf
	v_fmac_f32_dpp v233, v57, v161 row_shl:14 row_mask:0xf bank_mask:0xf
	v_fmac_f32_dpp v234, v44, v192 row_shl:14 row_mask:0xf bank_mask:0xf
	v_fmac_f32_dpp v235, v45, v193 row_shl:14 row_mask:0xf bank_mask:0xf
	v_mul_f32_e32 v246, v236, v232
	v_mul_f32_e32 v247, v236, v233
	v_exp_f32_e32 v246, v246
	v_exp_f32_e32 v247, v247
	s_nop 0
	v_pk_add_f32 v[246:247], v[246:247], v[238:239]
	v_rcp_f32_e32 v246, v246
	v_rcp_f32_e32 v247, v247
	v_pk_mul_f32 v[232:233], v[232:233], v[234:235]
	v_pk_mul_f32 v[232:233], v[232:233], v[246:247]
	v_cvt_pk_bf16_f32 v50, v232, v233
	v_pk_fma_f32 v[232:233], v[56:57], v[176:177], v[184:185]
	v_pk_fma_f32 v[234:235], v[44:45], v[208:209], v[216:217]
	s_nop 1
	v_fmac_f32_dpp v232, v56, v168 row_shr:1 row_mask:0xf bank_mask:0xf
	v_fmac_f32_dpp v233, v57, v169 row_shr:1 row_mask:0xf bank_mask:0xf
	v_fmac_f32_dpp v234, v44, v200 row_shr:1 row_mask:0xf bank_mask:0xf
	v_fmac_f32_dpp v235, v45, v201 row_shr:1 row_mask:0xf bank_mask:0xf
	v_fmac_f32_dpp v232, v56, v160 row_shr:2 row_mask:0xf bank_mask:0xf
	v_fmac_f32_dpp v233, v57, v161 row_shr:2 row_mask:0xf bank_mask:0xf
	v_fmac_f32_dpp v234, v44, v192 row_shr:2 row_mask:0xf bank_mask:0xf
; __device__ __forceinline__ unsigned cvt_pk_bf16(float lo, float hi) { unsigned r; asm("v_cvt_pk_bf16_f32 %0, %1, %2" : "=v"(r) : "v"(lo), "v"(hi)); return r; }
; __device__ __forceinline__ float sigmoid_f(float v) { return __builtin_amdgcn_rcpf(1.0f + __builtin_amdgcn_exp2f(-1.4426950409f * v)); }
; __device__ __forceinline__ u32x4 pack8(f32x4 a, f32x4 b) { u32x4 w; w.x = cvt_pk_bf16(a[0], a[1]); w.y = cvt_pk_bf16(a[2], a[3]); w.z = cvt_pk_bf16(b[0], b[1]); w.w = cvt_pk_bf16(b[2], b[3]); return w; }
; __device__ __forceinline__ f32x4 bf4(u32x2 w) { return (f32x4){bf_lo(w.x), bf_hi(w.x), bf_lo(w.y), bf_hi(w.y)}; }
;     __device__ __forceinline__ void operator()(const f32x4 (&acc)[2][2][4][2], const Unit& u, int wr, int wc, int fr, int fq) const {
;         const int row0 = u.pm * BM + wr * 64 + fr, c0 = u.pn * BM + wc * 32 + 8 * fq;
; #pragma unroll
;         for (int ai = 0; ai < 2; ++ai)
; #pragma unroll
;             for (int m = 0; m < 4; ++m) { const int row = row0 + ai * HALF + m * 16; bf16_t* rowp = UP + (size_t)row * 5632 + u.pn * HALF + wc * 32 + 8 * fq;
; #pragma unroll
;                 for (int bj = 0; bj < 2; ++bj) { const u32x4 w = pack8(acc[ai][bj][m][0], acc[ai][bj][m][1]); __builtin_nontemporal_store(w, (u32x4*)(rowp + (size_t)bj * ((size_t)16384 * 5632)));
;                     if (m == 3 && fr >= 14) *(u32x4*)(HALO + ((size_t)(row >> 6) * 2 + (fr - 14)) * 11264 + c0 + bj * HALF) = w; } }
;     }
; __device__ __forceinline__ void phase10(const Args& a, int G, int wv, bool dummy = false) {
;     ...
;             for (int t = 0; t < 8; ++t) { const f32x4 gc = bf4(gr[t]), vc = bf4(vr[t]);
;                 const f32x4 gg = wg0 * gm2 + wg1 * gm1 + wg2 * gc + bg, vv = wv0 * vm2 + wv1 * vm1 + wv2 * vc + bv;
;                 f32x4 o;
; #pragma unroll
;                 for (int e = 0; e < 4; ++e) o[e] = gg[e] * pg8::sigmoid_f(gg[e]) * vv[e];
;                 u32x2 w; w.x = cvt_pk_bf16(o[0], o[1]); w.y = cvt_pk_bf16(o[2], o[3]);
;                 if (dummy) *(u32x2*)((bf16_t*)(a.ws + WS_D) + ((((size_t)(row0 + t0 + t)) * 5632 + ch) & (size_t)0x1ffffff)) = w; else *(u32x2*)(up + (size_t)(t0 + t) * 5632) = w;
;                 gm2 = gm1; gm1 = gc; vm2 = vm1; vm1 = vc; }
	v_fmac_f32_dpp v235, v45, v193 row_shr:2 row_mask:0xf bank_mask:0xf
	v_mul_f32_e32 v246, v236, v232
	v_mul_f32_e32 v247, v236, v233
	v_exp_f32_e32 v246, v246
	v_exp_f32_e32 v247, v247
	s_nop 0
	v_pk_add_f32 v[246:247], v[246:247], v[238:239]
	v_rcp_f32_e32 v246, v246
	v_rcp_f32_e32 v247, v247
	v_pk_mul_f32 v[232:233], v[232:233], v[234:235]
	v_pk_mul_f32 v[232:233], v[232:233], v[246:247]
	v_cvt_pk_bf16_f32 v62, v232, v233
	v_pk_fma_f32 v[232:233], v[10:11], v[178:179], v[186:187]
	v_pk_fma_f32 v[234:235], v[2:3], v[210:211], v[218:219]
	s_nop 1
	v_fmac_f32_dpp v232, v10, v170 row_shr:1 row_mask:0xf bank_mask:0xf
	v_fmac_f32_dpp v233, v11, v171 row_shr:1 row_mask:0xf bank_mask:0xf
	v_fmac_f32_dpp v234, v2, v202 row_shr:1 row_mask:0xf bank_mask:0xf
	v_fmac_f32_dpp v235, v3, v203 row_shr:1 row_mask:0xf bank_mask:0xf
	v_fmac_f32_dpp v232, v10, v162 row_shr:2 row_mask:0xf bank_mask:0xf
	v_fmac_f32_dpp v233, v11, v163 row_shr:2 row_mask:0xf bank_mask:0xf
	v_fmac_f32_dpp v234, v2, v194 row_shr:2 row_mask:0xf bank_mask:0xf
	v_fmac_f32_dpp v235, v3, v195 row_shr:2 row_mask:0xf bank_mask:0xf
	v_fmac_f32_dpp v232, v26, v170 row_shl:15 row_mask:0xf bank_mask:0xf
	v_fmac_f32_dpp v233, v27, v171 row_shl:15 row_mask:0xf bank_mask:0xf
	v_fmac_f32_dpp v234, v14, v202 row_shl:15 row_mask:0xf bank_mask:0xf
	v_fmac_f32_dpp v235, v15, v203 row_shl:15 row_mask:0xf bank_mask:0xf
	v_fmac_f32_dpp v232, v26, v162 row_shl:14 row_mask:0xf bank_mask:0xf
	v_fmac_f32_dpp v233, v27, v163 row_shl:14 row_mask:0xf bank_mask:0xf
	v_fmac_f32_dpp v234, v14, v194 row_shl:14 row_mask:0xf bank_mask:0xf
	v_fmac_f32_dpp v235, v15, v195 row_shl:14 row_mask:0xf bank_mask:0xf
	v_mul_f32_e32 v246, v236, v232
	v_mul_f32_e32 v247, v236, v233
	v_exp_f32_e32 v246, v246
	v_exp_f32_e32 v247, v247
	s_nop 0
	v_pk_add_f32 v[246:247], v[246:247], v[238:239]
	v_rcp_f32_e32 v246, v246
	v_rcp_f32_e32 v247, v247
	v_pk_mul_f32 v[232:233], v[232:233], v[234:235]
	v_pk_mul_f32 v[232:233], v[232:233], v[246:247]
	v_cvt_pk_bf16_f32 v19, v232, v233
	v_pk_fma_f32 v[232:233], v[26:27], v[178:179], v[186:187]
	v_pk_fma_f32 v[234:235], v[14:15], v[210:211], v[218:219]
	s_nop 1
	v_fmac_f32_dpp v232, v26, v170 row_shr:1 row_mask:0xf bank_mask:0xf
	v_fmac_f32_dpp v233, v27, v171 row_shr:1 row_mask:0xf bank_mask:0xf
	v_fmac_f32_dpp v234, v14, v202 row_shr:1 row_mask:0xf bank_mask:0xf
	v_fmac_f32_dpp v235, v15, v203 row_shr:1 row_mask:0xf bank_mask:0xf
	v_fmac_f32_dpp v232, v26, v162 row_shr:2 row_mask:0xf bank_mask:0xf
	v_fmac_f32_dpp v233, v27, v163 row_shr:2 row_mask:0xf bank_mask:0xf
	v_fmac_f32_dpp v234, v14, v194 row_shr:2 row_mask:0xf bank_mask:0xf
	v_fmac_f32_dpp v235, v15, v195 row_shr:2 row_mask:0xf bank_mask:0xf
	v_fmac_f32_dpp v232, v42, v170 row_shl:15 row_mask:0xf bank_mask:0xf
	v_fmac_f32_dpp v233, v43, v171 row_shl:15 row_mask:0xf bank_mask:0xf
	v_fmac_f32_dpp v234, v30, v202 row_shl:15 row_mask:0xf bank_mask:0xf
	v_fmac_f32_dpp v235, v31, v203 row_shl:15 row_mask:0xf bank_mask:0xf
	v_fmac_f32_dpp v232, v42, v162 row_shl:14 row_mask:0xf bank_mask:0xf
	v_fmac_f32_dpp v233, v43, v163 row_shl:14 row_mask:0xf bank_mask:0xf
	v_fmac_f32_dpp v234, v30, v194 row_shl:14 row_mask:0xf bank_mask:0xf
	v_fmac_f32_dpp v235, v31, v195 row_shl:14 row_mask:0xf bank_mask:0xf
	v_mul_f32_e32 v246, v236, v232
	v_mul_f32_e32 v247, v236, v233
	v_exp_f32_e32 v246, v246
	v_exp_f32_e32 v247, v247
	s_nop 0
	v_pk_add_f32 v[246:247], v[246:247], v[238:239]
	v_rcp_f32_e32 v246, v246
	v_rcp_f32_e32 v247, v247
	v_pk_mul_f32 v[232:233], v[232:233], v[234:235]
	v_pk_mul_f32 v[232:233], v[232:233], v[246:247]
	v_cvt_pk_bf16_f32 v35, v232, v233
	v_pk_fma_f32 v[232:233], v[42:43], v[178:179], v[186:187]
	v_pk_fma_f32 v[234:235], v[30:31], v[210:211], v[218:219]
	s_nop 1
	v_fmac_f32_dpp v232, v42, v170 row_shr:1 row_mask:0xf bank_mask:0xf
	v_fmac_f32_dpp v233, v43, v171 row_shr:1 row_mask:0xf bank_mask:0xf
	v_fmac_f32_dpp v234, v30, v202 row_shr:1 row_mask:0xf bank_mask:0xf
	v_fmac_f32_dpp v235, v31, v203 row_shr:1 row_mask:0xf bank_mask:0xf
	v_fmac_f32_dpp v232, v42, v162 row_shr:2 row_mask:0xf bank_mask:0xf
	v_fmac_f32_dpp v233, v43, v163 row_shr:2 row_mask:0xf bank_mask:0xf
	v_fmac_f32_dpp v234, v30, v194 row_shr:2 row_mask:0xf bank_mask:0xf
	v_fmac_f32_dpp v235, v31, v195 row_shr:2 row_mask:0xf bank_mask:0xf
	v_fmac_f32_dpp v232, v58, v170 row_shl:15 row_mask:0xf bank_mask:0xf
	v_fmac_f32_dpp v233, v59, v171 row_shl:15 row_mask:0xf bank_mask:0xf
	v_fmac_f32_dpp v234, v46, v202 row_shl:15 row_mask:0xf bank_mask:0xf
	v_fmac_f32_dpp v235, v47, v203 row_shl:15 row_mask:0xf bank_mask:0xf
	v_fmac_f32_dpp v232, v58, v162 row_shl:14 row_mask:0xf bank_mask:0xf
	v_fmac_f32_dpp v233, v59, v163 row_shl:14 row_mask:0xf bank_mask:0xf
	v_fmac_f32_dpp v234, v46, v194 row_shl:14 row_mask:0xf bank_mask:0xf
	v_fmac_f32_dpp v235, v47, v195 row_shl:14 row_mask:0xf bank_mask:0xf
	v_mul_f32_e32 v246, v236, v232
	v_mul_f32_e32 v247, v236, v233
	v_exp_f32_e32 v246, v246
	v_exp_f32_e32 v247, v247
	s_nop 0
	v_pk_add_f32 v[246:247], v[246:247], v[238:239]
	v_rcp_f32_e32 v246, v246
	v_rcp_f32_e32 v247, v247
	v_pk_mul_f32 v[232:233], v[232:233], v[234:235]
	v_pk_mul_f32 v[232:233], v[232:233], v[246:247]
	v_cvt_pk_bf16_f32 v51, v232, v233
	v_pk_fma_f32 v[232:233], v[58:59], v[178:179], v[186:187]
	v_pk_fma_f32 v[234:235], v[46:47], v[210:211], v[218:219]
	s_nop 1
	v_fmac_f32_dpp v232, v58, v170 row_shr:1 row_mask:0xf bank_mask:0xf
	v_fmac_f32_dpp v233, v59, v171 row_shr:1 row_mask:0xf bank_mask:0xf
	v_fmac_f32_dpp v234, v46, v202 row_shr:1 row_mask:0xf bank_mask:0xf
	v_fmac_f32_dpp v235, v47, v203 row_shr:1 row_mask:0xf bank_mask:0xf
	v_fmac_f32_dpp v232, v58, v162 row_shr:2 row_mask:0xf bank_mask:0xf
	v_fmac_f32_dpp v233, v59, v163 row_shr:2 row_mask:0xf bank_mask:0xf
	v_fmac_f32_dpp v234, v46, v194 row_shr:2 row_mask:0xf bank_mask:0xf
	v_fmac_f32_dpp v235, v47, v195 row_shr:2 row_mask:0xf bank_mask:0xf
	v_mul_f32_e32 v246, v236, v232
	v_mul_f32_e32 v247, v236, v233
	v_exp_f32_e32 v246, v246
	v_exp_f32_e32 v247, v247
	s_nop 0
	v_pk_add_f32 v[246:247], v[246:247], v[238:239]
	v_rcp_f32_e32 v246, v246
	v_rcp_f32_e32 v247, v247
	v_pk_mul_f32 v[232:233], v[232:233], v[234:235]
	v_pk_mul_f32 v[232:233], v[232:233], v[246:247]
	v_cvt_pk_bf16_f32 v63, v232, v233
	s_add_u32 s36, s100, 0x160000
	s_addc_u32 s37, s101, 0
	s_andn2_b64 exec, exec, s[64:65]
	global_store_dwordx4 v149, v[60:63], s[36:37]
	s_mov_b64 exec, -1
	s_add_u32 s36, s100, 0x18c000
	s_addc_u32 s37, s101, 0
	global_store_dwordx4 v149, v[48:51], s[36:37]
	s_add_u32 s36, s100, 0x1b8000
	s_addc_u32 s37, s101, 0
	global_store_dwordx4 v149, v[32:35], s[36:37]
	s_add_u32 s36, s100, 0x1e4000
	s_addc_u32 s37, s101, 0
	global_store_dwordx4 v149, v[16:19], s[36:37]
	s_andn2_b64 vcc, exec, s[4:5]
	s_mov_b64 s[4:5], -1
	s_cbranch_vccnz .LBB0_961
	s_andn2_b64 vcc, exec, s[10:11]
	s_cbranch_vccnz .LBB0_960
	s_barrier
	s_branch .LBB0_960

; __device__ __forceinline__ f32x4 bf4(u32x2 w) { return (f32x4){bf_lo(w.x), bf_hi(w.x), bf_lo(w.y), bf_hi(w.y)}; }
; __device__ __forceinline__ void phase10(const Args& a, int G, int wv, bool dummy = false) {
;     ...
;     for (int it = gw; it < 256 * 22; it += NGW) {
;         const int rs = it / 22, cs = it % 22, row0 = rs * 64, pn = 2 * cs + (lane >> 5), j = (lane & 31) * 4, col = 256 * pn + j, ch = 128 * pn + j; constexpr size_t VPL = (size_t)16384 * 5632;
;         const f32x4 wg0 = *(const f32x4*)(cw + ch), wg1 = *(const f32x4*)(cw + 11264 + ch), wg2 = *(const f32x4*)(cw + 22528 + ch), bg = *(const f32x4*)(cb + ch);
;         const f32x4 wv0 = *(const f32x4*)(cw + 5632 + ch), wv1 = *(const f32x4*)(cw + 11264 + 5632 + ch), wv2 = *(const f32x4*)(cw + 22528 + 5632 + ch), bv = *(const f32x4*)(cb + 5632 + ch);
;         f32x4 gm2 = {0.f, 0.f, 0.f, 0.f}, gm1 = gm2, vm2 = gm2, vm1 = gm2;
;         if (row0 & 2047) { const bf16_t* hp = HALO + (size_t)(rs - 1) * 2 * 11264 + col;
;             gm2 = bf4(*(const u32x2*)hp); gm1 = bf4(*(const u32x2*)(hp + 11264)); vm2 = bf4(*(const u32x2*)(hp + 128)); vm1 = bf4(*(const u32x2*)(hp + 11264 + 128)); }
;         bf16_t* up = UP + (size_t)row0 * 5632 + ch;
.LBB0_1034:
	s_cmp_lt_i32 s82, 11
	s_cselect_b64 s[4:5], -1, 0
	s_and_b64 s[2:3], s[4:5], s[2:3]
	s_andn2_b64 vcc, exec, s[2:3]
	s_cbranch_vccnz .LBB0_1043
	v_mbcnt_lo_u32_b32 v0, -1, 0
	v_mbcnt_hi_u32_b32 v0, -1, v0
	s_lshl_b32 s5, s33, 3
	s_waitcnt lgkmcnt(0)
	v_or_b32_e32 v1, s90, v0
	s_nop 0
	v_readfirstlane_b32 s4, v1
	s_ashr_i32 s4, s4, 6
	s_add_i32 s22, s4, s5
	s_cmpk_gt_i32 s22, 0x15ff
	s_cbranch_scc1 .LBB0_1043
	s_load_dwordx4 s[4:7], s[0:1], 0xa8
	s_lshl_b32 s23, s89, 3
	s_add_u32 s24, s78, 0x1f300000
	s_addc_u32 s25, s79, 0
	v_bfe_u32 v70, v0, 5, 1
	s_waitcnt lgkmcnt(0)
	s_add_u32 s8, s4, 0xb000
	s_addc_u32 s9, s5, 0
	s_add_u32 s12, s4, 0x16000
	s_addc_u32 s13, s5, 0
	s_add_u32 s14, s4, 0x5800
	s_addc_u32 s15, s5, 0
	s_add_u32 s16, s4, 0x10800
	s_addc_u32 s17, s5, 0
	s_add_u32 s18, s4, 0x1b800
	s_addc_u32 s19, s5, 0
	s_add_u32 s20, s6, 0x5800
	s_addc_u32 s21, s7, 0
	v_lshlrev_b32_e32 v0, 2, v0
	s_add_u32 s26, s78, 0x14300000
	v_and_b32_e32 v71, 0x7c, v0
	s_addc_u32 s27, s79, 0
	v_mov_b32_e32 v0, 0
	s_mov_b32 s28, 0xffff0000
	s_movk_i32 s29, 0x5000
	s_add_u32 s10, s78, 0x9300000
	s_addc_u32 s11, s79, 0
.LBB0_1037:
	s_mul_hi_i32 s30, s22, 0x2e8ba2e9
	s_lshr_b32 s31, s30, 31
	s_ashr_i32 s30, s30, 2
	s_add_i32 s30, s30, s31
	s_mul_i32 s31, s30, 22
	s_sub_i32 s31, s22, s31
	v_lshl_or_b32 v1, s31, 1, v70
	v_lshl_or_b32 v58, v1, 7, v71
	v_lshlrev_b32_e32 v2, 2, v58
	global_load_dwordx4 v[4:7], v2, s[4:5]
	global_load_dwordx4 v[8:11], v2, s[8:9]
	global_load_dwordx4 v[12:15], v2, s[12:13]
	global_load_dwordx4 v[16:19], v2, s[6:7]
	global_load_dwordx4 v[20:23], v2, s[14:15]
	global_load_dwordx4 v[24:27], v2, s[16:17]
	global_load_dwordx4 v[28:31], v2, s[18:19]
	global_load_dwordx4 v[32:35], v2, s[20:21]
	v_lshl_or_b32 v3, v1, 8, v71
	v_lshlrev_b32_e32 v3, 1, v3
	s_mul_i32 s34, s30, 0xb000
	s_add_u32 s28, s26, s34
	s_addc_u32 s29, s27, 0
	global_load_dwordx2 v[44:45], v3, s[28:29]
	global_load_dwordx2 v[46:47], v3, s[28:29] offset:256
	s_add_u32 s28, s28, 0x5800
	s_addc_u32 s29, s29, 0
	global_load_dwordx2 v[48:49], v3, s[28:29]
	global_load_dwordx2 v[50:51], v3, s[28:29] offset:256
	v_mov_b32_e32 v36, 0
	v_mov_b32_e32 v37, 0
	v_mov_b32_e32 v38, 0
	v_mov_b32_e32 v39, 0
	v_mov_b32_e32 v40, 0
	v_mov_b32_e32 v41, 0
	v_mov_b32_e32 v42, 0
	v_mov_b32_e32 v43, 0
	s_and_b32 s35, s30, 31
	s_cmp_eq_u32 s35, 0
	s_cbranch_scc1 .Lfix_nohalo
	s_add_u32 s28, s24, s34
	s_addc_u32 s29, s25, 0
	s_sub_u32 s28, s28, 0xb000
	s_subb_u32 s29, s29, 0
	global_load_dwordx2 v[36:37], v3, s[28:29]
	global_load_dwordx2 v[38:39], v3, s[28:29] offset:256
	s_add_u32 s28, s28, 0x5800
	s_addc_u32 s29, s29, 0
	global_load_dwordx2 v[40:41], v3, s[28:29]
	global_load_dwordx2 v[42:43], v3, s[28:29] offset:256
; __device__ __forceinline__ unsigned cvt_pk_bf16(float lo, float hi) { unsigned r; asm("v_cvt_pk_bf16_f32 %0, %1, %2" : "=v"(r) : "v"(lo), "v"(hi)); return r; }
; __device__ __forceinline__ float sigmoid_f(float v) { return __builtin_amdgcn_rcpf(1.0f + __builtin_amdgcn_exp2f(-1.4426950409f * v)); }
; __device__ __forceinline__ f32x4 bf4(u32x2 w) { return (f32x4){bf_lo(w.x), bf_hi(w.x), bf_lo(w.y), bf_hi(w.y)}; }
; __device__ __forceinline__ void phase10(const Args& a, int G, int wv, bool dummy = false) {
;     ...
;             for (int t = 0; t < 8; ++t) { const f32x4 gc = bf4(gr[t]), vc = bf4(vr[t]);
;                 const f32x4 gg = wg0 * gm2 + wg1 * gm1 + wg2 * gc + bg, vv = wv0 * vm2 + wv1 * vm1 + wv2 * vc + bv;
;                 f32x4 o;
; #pragma unroll
;                 for (int e = 0; e < 4; ++e) o[e] = gg[e] * pg8::sigmoid_f(gg[e]) * vv[e];
;                 u32x2 w; w.x = cvt_pk_bf16(o[0], o[1]); w.y = cvt_pk_bf16(o[2], o[3]);
;                 if (dummy) *(u32x2*)((bf16_t*)(a.ws + WS_D) + ((((size_t)(row0 + t0 + t)) * 5632 + ch) & (size_t)0x1ffffff)) = w; else *(u32x2*)(up + (size_t)(t0 + t) * 5632) = w;
;                 gm2 = gm1; gm1 = gc; vm2 = vm1; vm1 = vc; }
.Lfix_nohalo:
	s_waitcnt vmcnt(0)
	v_lshlrev_b32_e32 v120, 16, v36
	v_and_b32_e32 v121, 0xffff0000, v36
	v_lshlrev_b32_e32 v122, 16, v37
	v_and_b32_e32 v123, 0xffff0000, v37
	v_lshlrev_b32_e32 v124, 16, v38
	v_and_b32_e32 v125, 0xffff0000, v38
	v_lshlrev_b32_e32 v126, 16, v39
	v_and_b32_e32 v127, 0xffff0000, v39
	v_lshlrev_b32_e32 v128, 16, v40
	v_and_b32_e32 v129, 0xffff0000, v40
	v_lshlrev_b32_e32 v130, 16, v41
	v_and_b32_e32 v131, 0xffff0000, v41
	v_lshlrev_b32_e32 v132, 16, v42
	v_and_b32_e32 v133, 0xffff0000, v42
	v_lshlrev_b32_e32 v134, 16, v43
	v_and_b32_e32 v135, 0xffff0000, v43
	v_lshlrev_b32_e32 v136, 16, v44
	v_and_b32_e32 v137, 0xffff0000, v44
	v_lshlrev_b32_e32 v138, 16, v45
	v_and_b32_e32 v139, 0xffff0000, v45
	v_lshlrev_b32_e32 v140, 16, v46
	v_and_b32_e32 v141, 0xffff0000, v46
	v_lshlrev_b32_e32 v142, 16, v47
	v_and_b32_e32 v143, 0xffff0000, v47
	v_lshlrev_b32_e32 v144, 16, v48
	v_and_b32_e32 v145, 0xffff0000, v48
	v_lshlrev_b32_e32 v146, 16, v49
	v_and_b32_e32 v147, 0xffff0000, v49
	v_lshlrev_b32_e32 v148, 16, v50
	v_and_b32_e32 v149, 0xffff0000, v50
	v_lshlrev_b32_e32 v150, 16, v51
	v_and_b32_e32 v151, 0xffff0000, v51
	v_mul_f32_e32 v152, v8, v128
	v_fmac_f32_e32 v152, v4, v120
	v_fmac_f32_e32 v152, v12, v136
	v_add_f32_e32 v152, v16, v152
	v_mul_f32_e32 v153, v9, v129
	v_fmac_f32_e32 v153, v5, v121
	v_fmac_f32_e32 v153, v13, v137
	v_add_f32_e32 v153, v17, v153
	v_mul_f32_e32 v154, v10, v130
	v_fmac_f32_e32 v154, v6, v122
	v_fmac_f32_e32 v154, v14, v138
	v_add_f32_e32 v154, v18, v154
	v_mul_f32_e32 v155, v11, v131
	v_fmac_f32_e32 v155, v7, v123
	v_fmac_f32_e32 v155, v15, v139
	v_add_f32_e32 v155, v19, v155
	v_mul_f32_e32 v156, v24, v132
	v_fmac_f32_e32 v156, v20, v124
	v_fmac_f32_e32 v156, v28, v140
	v_add_f32_e32 v156, v32, v156
	v_mul_f32_e32 v157, v25, v133
	v_fmac_f32_e32 v157, v21, v125
	v_fmac_f32_e32 v157, v29, v141
	v_add_f32_e32 v157, v33, v157
	v_mul_f32_e32 v158, v26, v134
	v_fmac_f32_e32 v158, v22, v126
	v_fmac_f32_e32 v158, v30, v142
	v_add_f32_e32 v158, v34, v158
	v_mul_f32_e32 v159, v27, v135
	v_fmac_f32_e32 v159, v23, v127
	v_fmac_f32_e32 v159, v31, v143
	v_add_f32_e32 v159, v35, v159
	v_mul_f32_e32 v160, v8, v136
	v_fmac_f32_e32 v160, v4, v128
	v_fmac_f32_e32 v160, v12, v144
	v_add_f32_e32 v160, v16, v160
	v_mul_f32_e32 v161, v9, v137
	v_fmac_f32_e32 v161, v5, v129
	v_fmac_f32_e32 v161, v13, v145
	v_add_f32_e32 v161, v17, v161
	v_mul_f32_e32 v162, v10, v138
	v_fmac_f32_e32 v162, v6, v130
	v_fmac_f32_e32 v162, v14, v146
	v_add_f32_e32 v162, v18, v162
	v_mul_f32_e32 v163, v11, v139
	v_fmac_f32_e32 v163, v7, v131
	v_fmac_f32_e32 v163, v15, v147
	v_add_f32_e32 v163, v19, v163
	v_mul_f32_e32 v164, v24, v140
	v_fmac_f32_e32 v164, v20, v132
	v_fmac_f32_e32 v164, v28, v148
	v_add_f32_e32 v164, v32, v164
	v_mul_f32_e32 v165, v25, v141
	v_fmac_f32_e32 v165, v21, v133
	v_fmac_f32_e32 v165, v29, v149
	v_add_f32_e32 v165, v33, v165
	v_mul_f32_e32 v166, v26, v142
	v_fmac_f32_e32 v166, v22, v134
	v_fmac_f32_e32 v166, v30, v150
	v_add_f32_e32 v166, v34, v166
	v_mul_f32_e32 v167, v27, v143
	v_fmac_f32_e32 v167, v23, v135
	v_fmac_f32_e32 v167, v31, v151
	v_add_f32_e32 v167, v35, v167
	v_mul_f32_e32 v168, 0xbfb8aa3b, v152
	v_exp_f32_e32 v168, v168
	v_mul_f32_e32 v169, 0xbfb8aa3b, v153
	v_exp_f32_e32 v169, v169
	v_mul_f32_e32 v170, 0xbfb8aa3b, v154
	v_exp_f32_e32 v170, v170
	v_mul_f32_e32 v171, 0xbfb8aa3b, v155
	v_exp_f32_e32 v171, v171
	s_nop 0
	v_add_f32_e32 v168, 1.0, v168
	v_rcp_f32_e32 v168, v168
	v_add_f32_e32 v169, 1.0, v169
	v_rcp_f32_e32 v169, v169
	v_add_f32_e32 v170, 1.0, v170
	v_rcp_f32_e32 v170, v170
	v_add_f32_e32 v171, 1.0, v171
	v_rcp_f32_e32 v171, v171
	s_nop 0
	v_mul_f32_e32 v152, v152, v168
	v_mul_f32_e32 v152, v152, v156
	v_mul_f32_e32 v153, v153, v169
	v_mul_f32_e32 v153, v153, v157
	v_mul_f32_e32 v154, v154, v170
	v_mul_f32_e32 v154, v154, v158
	v_mul_f32_e32 v155, v155, v171
	v_mul_f32_e32 v155, v155, v159
	v_mul_f32_e32 v172, 0xbfb8aa3b, v160
	v_exp_f32_e32 v172, v172
	v_mul_f32_e32 v173, 0xbfb8aa3b, v161
	v_exp_f32_e32 v173, v173
	v_mul_f32_e32 v174, 0xbfb8aa3b, v162
	v_exp_f32_e32 v174, v174
	v_mul_f32_e32 v175, 0xbfb8aa3b, v163
	v_exp_f32_e32 v175, v175
	s_nop 0
	v_add_f32_e32 v172, 1.0, v172
	v_rcp_f32_e32 v172, v172
	v_add_f32_e32 v173, 1.0, v173
	v_rcp_f32_e32 v173, v173
	v_add_f32_e32 v174, 1.0, v174
	v_rcp_f32_e32 v174, v174
	v_add_f32_e32 v175, 1.0, v175
	v_rcp_f32_e32 v175, v175
	s_nop 0
	v_mul_f32_e32 v160, v160, v172
	v_mul_f32_e32 v160, v160, v164
	v_mul_f32_e32 v161, v161, v173
	v_mul_f32_e32 v161, v161, v165
	v_mul_f32_e32 v162, v162, v174
	v_mul_f32_e32 v162, v162, v166
	v_mul_f32_e32 v163, v163, v175
	v_mul_f32_e32 v163, v163, v167
	v_cvt_pk_bf16_f32 v176, v152, v153
	v_cvt_pk_bf16_f32 v177, v154, v155
	v_cvt_pk_bf16_f32 v178, v160, v161
	v_cvt_pk_bf16_f32 v179, v162, v163
	v_lshlrev_b32_e32 v2, 1, v58
	s_mul_i32 s34, s30, 0xb0000
	s_mul_hi_u32 s35, s30, 0xb0000
	s_add_u32 s28, s10, s34
	s_addc_u32 s29, s11, s35
	global_store_dwordx2 v2, v[176:177], s[28:29]
	s_add_u32 s28, s28, 0x2c00
	s_addc_u32 s29, s29, 0
	global_store_dwordx2 v2, v[178:179], s[28:29]
	s_add_i32 s22, s22, s23
	s_cmpk_lt_i32 s22, 0x1600
	s_cbranch_scc1 .LBB0_1037

; __global__ void __launch_bounds__(512) fwd_kernel(Args a) {
	.amdhsa_kernel _Z10fwd_kernel4Args
		.amdhsa_group_segment_fixed_size 0
		.amdhsa_private_segment_fixed_size 0
		.amdhsa_kernarg_size 608
		.amdhsa_user_sgpr_count 2
		.amdhsa_user_sgpr_dispatch_ptr 0
		.amdhsa_user_sgpr_queue_ptr 0
		.amdhsa_user_sgpr_kernarg_segment_ptr 1
		.amdhsa_user_sgpr_dispatch_id 0
		.amdhsa_user_sgpr_kernarg_preload_length 0
		.amdhsa_user_sgpr_kernarg_preload_offset 0
		.amdhsa_user_sgpr_private_segment_size 0
		.amdhsa_uses_dynamic_stack 0
		.amdhsa_enable_private_segment 0
		.amdhsa_system_sgpr_workgroup_id_x 1
		.amdhsa_system_sgpr_workgroup_id_y 0
		.amdhsa_system_sgpr_workgroup_id_z 0
		.amdhsa_system_sgpr_workgroup_info 0
		.amdhsa_system_vgpr_workitem_id 2
		.amdhsa_next_free_vgpr 253
		.amdhsa_next_free_sgpr 102
		.amdhsa_accum_offset 256
		.amdhsa_reserve_vcc 1
		.amdhsa_float_round_mode_32 0
		.amdhsa_float_round_mode_16_64 0
		.amdhsa_float_denorm_mode_32 3
		.amdhsa_float_denorm_mode_16_64 3
		.amdhsa_dx10_clamp 1
		.amdhsa_ieee_mode 1
		.amdhsa_fp16_overflow 0
		.amdhsa_tg_split 0
		.amdhsa_exception_fp_ieee_invalid_op 0
		.amdhsa_exception_fp_denorm_src 0
		.amdhsa_exception_fp_ieee_div_zero 0
		.amdhsa_exception_fp_ieee_overflow 0
		.amdhsa_exception_fp_ieee_underflow 0
		.amdhsa_exception_fp_ieee_inexact 0
		.amdhsa_exception_int_div_zero 0
	.end_amdhsa_kernel

; __global__ void __launch_bounds__(512) fwd_kernel(Args a) {
amdhsa.kernels:
  - .agpr_count:     0
    .args:
      - .offset:         0
        .size:           352
        .value_kind:     by_value
      - .offset:         352
        .size:           4
        .value_kind:     hidden_block_count_x
      - .offset:         356
        .size:           4
        .value_kind:     hidden_block_count_y
      - .offset:         360
        .size:           4
        .value_kind:     hidden_block_count_z
      - .offset:         364
        .size:           2
        .value_kind:     hidden_group_size_x
      - .offset:         366
        .size:           2
        .value_kind:     hidden_group_size_y
      - .offset:         368
        .size:           2
        .value_kind:     hidden_group_size_z
      - .offset:         370
        .size:           2
        .value_kind:     hidden_remainder_x
      - .offset:         372
        .size:           2
        .value_kind:     hidden_remainder_y
      - .offset:         374
        .size:           2
        .value_kind:     hidden_remainder_z
      - .offset:         392
        .size:           8
        .value_kind:     hidden_global_offset_x
      - .offset:         400
        .size:           8
        .value_kind:     hidden_global_offset_y
      - .offset:         408
        .size:           8
        .value_kind:     hidden_global_offset_z
      - .offset:         416
        .size:           2
        .value_kind:     hidden_grid_dims
      - .offset:         440
        .size:           8
        .value_kind:     hidden_multigrid_sync_arg
      - .offset:         472
        .size:           4
        .value_kind:     hidden_dynamic_lds_size
    .group_segment_fixed_size: 0
    .kernarg_segment_align: 8
    .kernarg_segment_size: 608
    .language:       OpenCL C
    .language_version:
      - 2
      - 0
    .max_flat_workgroup_size: 512
    .name:           _Z10fwd_kernel4Args
    .private_segment_fixed_size: 0
    .sgpr_count:     108
    .sgpr_spill_count: 0
    .symbol:         _Z10fwd_kernel4Args.kd
    .uniform_work_group_size: 1
    .uses_dynamic_stack: false
    .vgpr_count:     253
    .vgpr_spill_count: 0
    .wavefront_size: 64
